# LDS-transposed coalesced bf16 epilogue (operand-swapped MFMA, ds_write_b64 -> ds_read_b128 -> global_store_dwordx4) in phases 8,12,17 and phase-1 in_even
# speedup vs baseline: 1.0153x; 1.0153x over previous
; DI bfr f2bf(float a) { return (bfr)(pack2(a, 0.f) & 0xffffu); }
; DI void phase_gemm_in_even(const Params& p, char* smem) {
;     ...
;   for (int t0 = blockIdx.x; t0 < NT1 + NT2; t0 += gridDim.x) {
;     const int t = (t0 < NT1 && (gridDim.x & 7) == 0) ? xcd_tile(t0, 14) : t0;
;     if (t < NT1) {
;       int mt = t / 14, nt = t % 14;
;       bfr* PB = p.PB;
;       gemm_tile<1024>(p.H, p.WtInE, 3712, 1024, mt * 128, nt * 256, smem,
;                 [=](int row, int col, float v) { PB[(size_t)row * EINP + col] = f2bf(v); });
.LBB0_116:
	s_cmpk_gt_i32 s46, 0x7ff
	s_cbranch_scc1 .LBB0_164
	s_load_dwordx2 s[0:1], s[92:93], 0xf8
	s_load_dwordx8 s[4:11], s[92:93], 0x170
	s_load_dwordx4 s[12:15], s[92:93], 0x1b8
	s_load_dwordx4 s[16:19], s[92:93], 0x148
	s_mov_b32 s3, 0
	s_waitcnt lgkmcnt(0)
	s_add_u32 s33, s0, 0x5394000
	s_addc_u32 s38, s1, 0
	s_add_u32 s39, s0, 0x4394000
	s_addc_u32 s40, s1, 0
	s_add_u32 s20, s14, 0x20000
	s_addc_u32 s21, s15, 0
	s_add_u32 s22, s12, 0x20000
	s_addc_u32 s23, s13, 0
	s_add_u32 s24, s10, 0x74000
	s_addc_u32 s25, s11, 0
	v_mov_b32_e32 v161, 0
	s_mov_b32 s41, 0x10000
	s_mov_b32 s42, 0x20000
	s_mov_b32 s43, 0x30000
	s_movk_i32 s44, 0x2000
	s_mov_b32 s45, 0xfffffc0
	s_movk_i32 s47, 0x80
	s_movk_i32 s48, 0x50
	s_mov_b64 s[26:27], 0x10000
	s_movk_i32 s49, 0x1a00
	s_mov_b32 s50, 0x3a000
	s_mov_b32 s51, 0x3c000
	s_mov_b32 s52, 0x3e000
	s_movk_i32 s53, 0x1c00
	s_movk_i32 s54, 0x1e00
	s_mov_b64 s[28:29], 0x3a000
	s_mov_b32 s55, s46
	s_branch .LBB0_120
.LBB0_119:
	v_readlane_b32 s0, v254, 0
	v_readlane_b32 s1, v254, 1
	s_load_dword s0, s[0:1], 0x10
	s_waitcnt lgkmcnt(0)
	s_lshr_b32 s0, s0, 16
	s_cmp_lg_u32 s0, 0
	s_cselect_b64 s[0:1], -1, 0
	s_cmp_lg_u64 s[0:1], 0
	s_addc_u32 s55, s55, s34
	s_cmpk_lt_i32 s55, 0x800
	s_cbranch_scc0 .LBB0_163

; #define GA_LOAD(pr_) do { _Pragma("unroll") for (int i = 0; i < 4; ++i) ra[i] = *(const u32x4*)(Ab + (i * 32) * lda + (pr_) * 64); } while (0)
; #define GB_LOAD(kt_) do { const bfr* bk_ = Bb + (kt_) * NB * 32; \
;     _Pragma("unroll") for (int i = 0; i < 4; ++i) rb[i] = *(const u32x4*)(bk_ + (i * 64) * 32); } while (0)
; #define G_STORE(kt_) do { bfr* as_ = S0 + ((kt_) & 1) * GSTAGE; bfr* bs_ = as_ + 128 * 40; \
;     if (apar == ((kt_) & 1)) { _Pragma("unroll") for (int i = 0; i < 4; ++i) *(u32x4*)(as_ + asoff + i * 32 * 40) = ra[i]; } \
;     _Pragma("unroll") for (int i = 0; i < 4; ++i) *(u32x4*)(bs_ + bsoff + i * 64 * 40) = rb[i]; } while (0)
; template <int lda>
; DI void gemm_mainloop(const bfr* __restrict__ A, const bfr* __restrict__ Bt, int NB, int K, int m0, int n0, char* smem, f32x16 (&acc)[2][4]) {
;     ...
;   const int nk = K >> 5;
;   const int arow = tid >> 3, ac8 = tid & 7, apar = ac8 >> 2;
;   const bfr* Ab = A + (m0 + arow) * lda + ac8 * 8;
;   const int asoff = arow * 40 + (ac8 & 3) * 8;
;   const int brow = tid >> 2, bc4 = tid & 3;
;   const bfr* Bb = Bt + (n0 + brow) * 32 + bc4 * 8;
;   const int bsoff = brow * 40 + bc4 * 8;
;     ...
;   GA_LOAD(0);
;   GB_LOAD(0);
;   G_STORE(0);
;   GB_LOAD(1);
;   __syncthreads();
; DI void phase_gemm_in_even(const Params& p, char* smem) {
;     ...
;       int mt = t / 14, nt = t % 14;
;       bfr* PB = p.PB;
;       gemm_tile<1024>(p.H, p.WtInE, 3712, 1024, mt * 128, nt * 256, smem,
.LBB0_151:
	s_andn2_b64 vcc, exec, s[0:1]
	s_cbranch_vccnz .LBB0_119
	s_mul_hi_i32 s0, s56, 0x92492493
	s_add_i32 s0, s0, s56
	s_lshr_b32 s1, s0, 31
	s_ashr_i32 s0, s0, 3
	s_add_i32 s0, s0, s1
	s_mul_i32 s1, s0, 14
	s_sub_i32 s1, s56, s1
	s_lshl_b32 s56, s0, 7
	s_lshl_b32 s2, s1, 8
	s_mov_b32 s57, 0
	s_mov_b64 s[30:31], 0
	s_lshl_b32 s98, s56, 11
	s_add_u32 s98, s16, s98
	s_addc_u32 s99, s17, 0
	s_lshl_b32 s100, s2, 6
	s_add_u32 s100, s10, s100
	s_addc_u32 s101, s11, 0
	v_writelane_b32 v188, s64, 0
	v_writelane_b32 v188, s65, 1
	v_writelane_b32 v188, s66, 2
	v_writelane_b32 v188, s67, 3
	v_writelane_b32 v188, s68, 4
	v_writelane_b32 v188, s69, 5
	v_writelane_b32 v188, s70, 6
	v_writelane_b32 v188, s71, 7
	v_writelane_b32 v188, s72, 8
	v_writelane_b32 v188, s73, 9
	v_writelane_b32 v188, s74, 10
	v_writelane_b32 v188, s75, 11
	v_writelane_b32 v188, s76, 12
	v_writelane_b32 v188, s77, 13
	v_writelane_b32 v188, s78, 14
	v_writelane_b32 v188, s79, 15
	s_mov_b32 s77, s56
	s_mov_b32 s78, s2
	v_lshrrev_b32_e32 v189, 6, v196
	v_and_b32_e32 v190, 63, v196
	v_readfirstlane_b32 s73, v189
	v_lshrrev_b32_e32 v191, 2, v190
	v_bfe_u32 v192, v190, 4, 2
	v_and_b32_e32 v189, 3, v190
	v_xor_b32_e32 v189, v189, v192
	v_lshlrev_b32_e32 v189, 4, v189
	v_lshl_add_u32 v160, v191, 11, v189
	v_add_u32_e32 v162, 0x8000, v160
	v_lshl_add_u32 v163, v191, 6, v189
	v_and_b32_e32 v191, 31, v190
	v_lshrrev_b32_e32 v192, 5, v190
	v_bfe_u32 v189, v190, 2, 2
	v_xor_b32_e32 v189, v189, v192
	v_lshlrev_b32_e32 v189, 4, v189
	v_lshl_add_u32 v180, v191, 6, v189
	s_lshr_b32 s74, s73, 1
	s_lshl_b32 s74, s74, 12
	s_and_b32 s75, s73, 1
	s_lshl_b32 s75, s75, 13
	v_add_u32_e32 v182, s75, v180
	v_add_u32_e32 v180, s74, v180
	v_xor_b32_e32 v183, 32, v182
	v_xor_b32_e32 v181, 32, v180
	s_lshl_b32 s74, s73, 16
	s_add_u32 s64, s98, s74
	s_addc_u32 s65, s99, 0
	s_lshl_b32 s74, s73, 12
	s_add_u32 s66, s100, s74
	s_addc_u32 s67, s101, 0
	s_lshl_b32 s68, s73, 11
	s_lshl_b32 s69, s73, 12
	s_mov_b32 s70, 0
	s_mov_b32 s71, 0
	s_mov_b32 s72, 0
	s_waitcnt lgkmcnt(0)
	s_barrier
	s_mul_i32 s74, s70, 0x6000
	s_add_u32 s75, s74, s68
	s_mov_b32 m0, s75
	s_add_u32 s76, s74, 0x2000
	s_cmp_eq_u32 s70, 2
	s_cselect_b32 s76, 0x10000, s76
	global_load_lds_dwordx4 v160, s[64:65]
	s_add_u32 m0, s75, 0x400
	s_add_u32 s76, s76, s69
	global_load_lds_dwordx4 v162, s[64:65]
	s_mov_b32 m0, s76
	s_add_u32 s64, s64, 64
	s_addc_u32 s65, s65, 0
	global_load_lds_dwordx4 v163, s[66:67]
	global_load_lds_dwordx4 v163, s[66:67] offset:1024
	global_load_lds_dwordx4 v163, s[66:67] offset:2048
	global_load_lds_dwordx4 v163, s[66:67] offset:3072
	s_add_u32 s66, s66, 0x3a000
	s_addc_u32 s67, s67, 0
	s_add_u32 s70, s70, 1
	s_cmp_eq_u32 s70, 3
	s_cselect_b32 s70, 0, s70
	s_mul_i32 s74, s70, 0x6000
	s_add_u32 s75, s74, s68
	s_mov_b32 m0, s75
	s_add_u32 s76, s74, 0x2000
	s_cmp_eq_u32 s70, 2
	s_cselect_b32 s76, 0x10000, s76
	global_load_lds_dwordx4 v160, s[64:65]
	s_add_u32 m0, s75, 0x400
	s_add_u32 s76, s76, s69
	global_load_lds_dwordx4 v162, s[64:65]
	s_mov_b32 m0, s76
	s_add_u32 s64, s64, 64
	s_addc_u32 s65, s65, 0
	global_load_lds_dwordx4 v163, s[66:67]
	global_load_lds_dwordx4 v163, s[66:67] offset:1024
	global_load_lds_dwordx4 v163, s[66:67] offset:2048
	global_load_lds_dwordx4 v163, s[66:67] offset:3072
	s_add_u32 s66, s66, 0x3a000
	s_addc_u32 s67, s67, 0
	s_add_u32 s70, s70, 1
	s_cmp_eq_u32 s70, 3
	s_cselect_b32 s70, 0, s70
	s_cmp_lt_u32 s46, 0x100
	s_cbranch_scc1 .Lp1e_nostag
	s_sleep 8

; #define MFMA32(a, b, c) __builtin_amdgcn_mfma_f32_32x32x16_bf16((a), (b), (c), 0, 0, 0)
; #define GA_LOAD(pr_) do { _Pragma("unroll") for (int i = 0; i < 4; ++i) ra[i] = *(const u32x4*)(Ab + (i * 32) * lda + (pr_) * 64); } while (0)
; #define GB_LOAD(kt_) do { const bfr* bk_ = Bb + (kt_) * NB * 32; \
;     _Pragma("unroll") for (int i = 0; i < 4; ++i) rb[i] = *(const u32x4*)(bk_ + (i * 64) * 32); } while (0)
; #define G_STORE(kt_) do { bfr* as_ = S0 + ((kt_) & 1) * GSTAGE; bfr* bs_ = as_ + 128 * 40; \
;     if (apar == ((kt_) & 1)) { _Pragma("unroll") for (int i = 0; i < 4; ++i) *(u32x4*)(as_ + asoff + i * 32 * 40) = ra[i]; } \
;     _Pragma("unroll") for (int i = 0; i < 4; ++i) *(u32x4*)(bs_ + bsoff + i * 64 * 40) = rb[i]; } while (0)
; template <int lda>
; DI void gemm_mainloop(const bfr* __restrict__ A, const bfr* __restrict__ Bt, int NB, int K, int m0, int n0, char* smem, f32x16 (&acc)[2][4]) {
;     ...
;   for (int kt = 0; kt < nk; ++kt) {
;     if (kt + 1 < nk) G_STORE(kt + 1);
;     if (kt + 2 < nk) {
;       GB_LOAD(kt + 2);
;       if ((kt & 1) == 0) GA_LOAD((kt >> 1) + 1);
;     }
;     const bfr* As = S0 + (kt & 1) * GSTAGE;
;     const bfr* Bs = As + 128 * 40;
; #pragma unroll
;     for (int ks = 0; ks < 2; ++ks) {
;       bf16x8 af[2], bfg[4];
; #pragma unroll
;       for (int i = 0; i < 2; ++i) af[i] = *(const bf16x8*)(As + (wr * 64 + i * 32 + r) * 40 + ks * 16 + hl * 8);
; #pragma unroll
;       for (int j = 0; j < 4; ++j) bfg[j] = *(const bf16x8*)(Bs + (wc * 128 + j * 32 + r) * 40 + ks * 16 + hl * 8);
; #pragma unroll
;       for (int i = 0; i < 2; ++i)
; #pragma unroll
;         for (int j = 0; j < 4; ++j) acc[i][j] = MFMA32(af[i], bfg[j], acc[i][j]);
;     }
;     __syncthreads();
;   }
.Lp1e_loop:
	s_waitcnt vmcnt(6)
	s_barrier
	s_mul_i32 s74, s71, 0x6000
	s_add_u32 s75, s74, 0x2000
	s_cmp_eq_u32 s71, 2
	s_cselect_b32 s75, 0x10000, s75
	v_add_u32_e32 v184, s74, v180
	v_add_u32_e32 v186, s75, v182
	v_add_u32_e32 v185, s74, v181
	v_add_u32_e32 v187, s75, v183
	ds_read_b128 v[128:131], v184
	ds_read_b128 v[144:147], v186
	ds_read_b128 v[148:151], v186 offset:2048
	ds_read_b128 v[152:155], v186 offset:4096
	ds_read_b128 v[156:159], v186 offset:6144
	ds_read_b128 v[132:135], v184 offset:2048
	ds_read_b128 v[136:139], v185
	ds_read_b128 v[164:167], v187
	ds_read_b128 v[168:171], v187 offset:2048
	ds_read_b128 v[172:175], v187 offset:4096
	ds_read_b128 v[176:179], v187 offset:6144
	ds_read_b128 v[140:143], v185 offset:2048
	s_add_u32 s71, s71, 1
	s_cmp_eq_u32 s71, 3
	s_cselect_b32 s71, 0, s71
	s_waitcnt lgkmcnt(10)
	v_mfma_f32_32x32x16_bf16 v[112:127], v[144:147], v[128:131], v[112:127]
	s_mul_i32 s74, s70, 0x6000
	s_add_u32 s75, s74, s68
	s_mov_b32 m0, s75
	s_add_u32 s76, s74, 0x2000
	s_cmp_eq_u32 s70, 2
	s_cselect_b32 s76, 0x10000, s76
	global_load_lds_dwordx4 v160, s[64:65]
	s_waitcnt lgkmcnt(9)
	v_mfma_f32_32x32x16_bf16 v[96:111], v[148:151], v[128:131], v[96:111]
	s_add_u32 m0, s75, 0x400
	s_add_u32 s76, s76, s69
	global_load_lds_dwordx4 v162, s[64:65]
	s_waitcnt lgkmcnt(8)
	v_mfma_f32_32x32x16_bf16 v[80:95], v[152:155], v[128:131], v[80:95]
	s_mov_b32 m0, s76
	s_add_u32 s64, s64, 64
	s_addc_u32 s65, s65, 0
	global_load_lds_dwordx4 v163, s[66:67]
	s_waitcnt lgkmcnt(7)
	v_mfma_f32_32x32x16_bf16 v[64:79], v[156:159], v[128:131], v[64:79]
	global_load_lds_dwordx4 v163, s[66:67] offset:1024
	s_waitcnt lgkmcnt(6)
	v_mfma_f32_32x32x16_bf16 v[48:63], v[144:147], v[132:135], v[48:63]
	global_load_lds_dwordx4 v163, s[66:67] offset:2048
	v_mfma_f32_32x32x16_bf16 v[32:47], v[148:151], v[132:135], v[32:47]
	global_load_lds_dwordx4 v163, s[66:67] offset:3072
	s_add_u32 s66, s66, 0x3a000
	s_addc_u32 s67, s67, 0
	v_mfma_f32_32x32x16_bf16 v[16:31], v[152:155], v[132:135], v[16:31]
	s_add_u32 s70, s70, 1
	s_cmp_eq_u32 s70, 3
	s_cselect_b32 s70, 0, s70
	v_mfma_f32_32x32x16_bf16 v[0:15], v[156:159], v[132:135], v[0:15]
	s_waitcnt lgkmcnt(4)
	v_mfma_f32_32x32x16_bf16 v[112:127], v[164:167], v[136:139], v[112:127]
	s_waitcnt lgkmcnt(3)
	v_mfma_f32_32x32x16_bf16 v[96:111], v[168:171], v[136:139], v[96:111]
	s_waitcnt lgkmcnt(2)
	v_mfma_f32_32x32x16_bf16 v[80:95], v[172:175], v[136:139], v[80:95]
	s_waitcnt lgkmcnt(1)
	v_mfma_f32_32x32x16_bf16 v[64:79], v[176:179], v[136:139], v[64:79]
	s_waitcnt lgkmcnt(0)
	v_mfma_f32_32x32x16_bf16 v[48:63], v[164:167], v[140:143], v[48:63]
	v_mfma_f32_32x32x16_bf16 v[32:47], v[168:171], v[140:143], v[32:47]
	v_mfma_f32_32x32x16_bf16 v[16:31], v[172:175], v[140:143], v[16:31]
	v_mfma_f32_32x32x16_bf16 v[0:15], v[176:179], v[140:143], v[0:15]
	s_add_u32 s72, s72, 1
	s_cmp_lt_u32 s72, 30
	s_cbranch_scc1 .Lp1e_loop
	s_waitcnt vmcnt(6)
	s_barrier
	s_mul_i32 s74, s71, 0x6000
	s_add_u32 s75, s74, 0x2000
	s_cmp_eq_u32 s71, 2
	s_cselect_b32 s75, 0x10000, s75
	v_add_u32_e32 v184, s74, v180
	v_add_u32_e32 v186, s75, v182
	v_add_u32_e32 v185, s74, v181
	v_add_u32_e32 v187, s75, v183
	ds_read_b128 v[128:131], v184
	ds_read_b128 v[144:147], v186
	ds_read_b128 v[148:151], v186 offset:2048
	ds_read_b128 v[152:155], v186 offset:4096
	ds_read_b128 v[156:159], v186 offset:6144
	ds_read_b128 v[132:135], v184 offset:2048
	ds_read_b128 v[136:139], v185
	ds_read_b128 v[164:167], v187
	ds_read_b128 v[168:171], v187 offset:2048
	ds_read_b128 v[172:175], v187 offset:4096
	ds_read_b128 v[176:179], v187 offset:6144
	ds_read_b128 v[140:143], v185 offset:2048
	s_add_u32 s71, s71, 1
	s_cmp_eq_u32 s71, 3
	s_cselect_b32 s71, 0, s71
	s_waitcnt lgkmcnt(10)
	v_mfma_f32_32x32x16_bf16 v[112:127], v[144:147], v[128:131], v[112:127]
	s_waitcnt lgkmcnt(9)
	v_mfma_f32_32x32x16_bf16 v[96:111], v[148:151], v[128:131], v[96:111]
	s_waitcnt lgkmcnt(8)
	v_mfma_f32_32x32x16_bf16 v[80:95], v[152:155], v[128:131], v[80:95]
	s_waitcnt lgkmcnt(7)
	v_mfma_f32_32x32x16_bf16 v[64:79], v[156:159], v[128:131], v[64:79]
	s_waitcnt lgkmcnt(6)
	v_mfma_f32_32x32x16_bf16 v[48:63], v[144:147], v[132:135], v[48:63]
	v_mfma_f32_32x32x16_bf16 v[32:47], v[148:151], v[132:135], v[32:47]
	v_mfma_f32_32x32x16_bf16 v[16:31], v[152:155], v[132:135], v[16:31]
	v_mfma_f32_32x32x16_bf16 v[0:15], v[156:159], v[132:135], v[0:15]
	s_waitcnt lgkmcnt(4)
	v_mfma_f32_32x32x16_bf16 v[112:127], v[164:167], v[136:139], v[112:127]
	s_waitcnt lgkmcnt(3)
	v_mfma_f32_32x32x16_bf16 v[96:111], v[168:171], v[136:139], v[96:111]
	s_waitcnt lgkmcnt(2)
	v_mfma_f32_32x32x16_bf16 v[80:95], v[172:175], v[136:139], v[80:95]
	s_waitcnt lgkmcnt(1)
	v_mfma_f32_32x32x16_bf16 v[64:79], v[176:179], v[136:139], v[64:79]
	s_waitcnt lgkmcnt(0)
	v_mfma_f32_32x32x16_bf16 v[48:63], v[164:167], v[140:143], v[48:63]
	v_mfma_f32_32x32x16_bf16 v[32:47], v[168:171], v[140:143], v[32:47]
	v_mfma_f32_32x32x16_bf16 v[16:31], v[172:175], v[140:143], v[16:31]
	v_mfma_f32_32x32x16_bf16 v[0:15], v[176:179], v[140:143], v[0:15]
	s_waitcnt vmcnt(0)
	s_barrier
; #define MFMA32(a, b, c) __builtin_amdgcn_mfma_f32_32x32x16_bf16((a), (b), (c), 0, 0, 0)
; DI int crow(int reg, int h) { return (reg & 3) + 8 * (reg >> 2) + 4 * h; }
; template <int lda>
; DI void gemm_mainloop(const bfr* __restrict__ A, const bfr* __restrict__ Bt, int NB, int K, int m0, int n0, char* smem, f32x16 (&acc)[2][4]) {
;     ...
;     const bfr* As = S0 + (kt & 1) * GSTAGE;
;     const bfr* Bs = As + 128 * 40;
; #pragma unroll
;     for (int ks = 0; ks < 2; ++ks) {
;       bf16x8 af[2], bfg[4];
; #pragma unroll
;       for (int i = 0; i < 2; ++i) af[i] = *(const bf16x8*)(As + (wr * 64 + i * 32 + r) * 40 + ks * 16 + hl * 8);
; #pragma unroll
;       for (int j = 0; j < 4; ++j) bfg[j] = *(const bf16x8*)(Bs + (wc * 128 + j * 32 + r) * 40 + ks * 16 + hl * 8);
; #pragma unroll
;       for (int i = 0; i < 2; ++i)
; #pragma unroll
;         for (int j = 0; j < 4; ++j) acc[i][j] = MFMA32(af[i], bfg[j], acc[i][j]);
; template <int lda, class Epi>
; DI void gemm_tile(const bfr* __restrict__ A, const bfr* __restrict__ Bt, int NB, int K, int m0, int n0, char* smem, Epi epi) {
;     ...
;   const int lane = tid3 & 63, wid = tid3 >> 6, wr = wid >> 1, wc = wid & 1, r = lane & 31, hl = lane >> 5;
; #pragma unroll
;   for (int i = 0; i < 2; ++i)
; #pragma unroll
;     for (int j = 0; j < 4; ++j)
; #pragma unroll
;       for (int q = 0; q < 16; ++q) {
;         int row = m0 + wr * 64 + i * 32 + crow(q, hl);
;         int col = n0 + wc * 128 + j * 32 + r;
;         epi(row, col, acc[i][j][q]);
;       }
	s_mul_i32 s74, s71, 0x6000
	s_add_u32 s75, s74, 0x2000
	s_cmp_eq_u32 s71, 2
	s_cselect_b32 s75, 0x10000, s75
	v_add_u32_e32 v184, s74, v180
	v_add_u32_e32 v186, s75, v182
	v_add_u32_e32 v185, s74, v181
	v_add_u32_e32 v187, s75, v183
	ds_read_b128 v[128:131], v184
	ds_read_b128 v[144:147], v186
	ds_read_b128 v[148:151], v186 offset:2048
	ds_read_b128 v[152:155], v186 offset:4096
	ds_read_b128 v[156:159], v186 offset:6144
	ds_read_b128 v[132:135], v184 offset:2048
	ds_read_b128 v[136:139], v185
	ds_read_b128 v[164:167], v187
	ds_read_b128 v[168:171], v187 offset:2048
	ds_read_b128 v[172:175], v187 offset:4096
	ds_read_b128 v[176:179], v187 offset:6144
	ds_read_b128 v[140:143], v185 offset:2048
	s_add_u32 s71, s71, 1
	s_cmp_eq_u32 s71, 3
	s_cselect_b32 s71, 0, s71
	s_waitcnt lgkmcnt(10)
	v_mfma_f32_32x32x16_bf16 v[112:127], v[144:147], v[128:131], v[112:127]
	s_waitcnt lgkmcnt(9)
	v_mfma_f32_32x32x16_bf16 v[96:111], v[148:151], v[128:131], v[96:111]
	s_waitcnt lgkmcnt(8)
	v_mfma_f32_32x32x16_bf16 v[80:95], v[152:155], v[128:131], v[80:95]
	s_waitcnt lgkmcnt(7)
	v_mfma_f32_32x32x16_bf16 v[64:79], v[156:159], v[128:131], v[64:79]
	s_waitcnt lgkmcnt(6)
	v_mfma_f32_32x32x16_bf16 v[48:63], v[144:147], v[132:135], v[48:63]
	v_mfma_f32_32x32x16_bf16 v[32:47], v[148:151], v[132:135], v[32:47]
	v_mfma_f32_32x32x16_bf16 v[16:31], v[152:155], v[132:135], v[16:31]
	v_mfma_f32_32x32x16_bf16 v[0:15], v[156:159], v[132:135], v[0:15]
	s_waitcnt lgkmcnt(4)
	v_mfma_f32_32x32x16_bf16 v[112:127], v[164:167], v[136:139], v[112:127]
	s_waitcnt lgkmcnt(3)
	v_mfma_f32_32x32x16_bf16 v[96:111], v[168:171], v[136:139], v[96:111]
	s_waitcnt lgkmcnt(2)
	v_mfma_f32_32x32x16_bf16 v[80:95], v[172:175], v[136:139], v[80:95]
	s_waitcnt lgkmcnt(1)
	v_mfma_f32_32x32x16_bf16 v[64:79], v[176:179], v[136:139], v[64:79]
	s_waitcnt lgkmcnt(0)
	v_mfma_f32_32x32x16_bf16 v[48:63], v[164:167], v[140:143], v[48:63]
	v_mfma_f32_32x32x16_bf16 v[32:47], v[168:171], v[140:143], v[32:47]
	v_mfma_f32_32x32x16_bf16 v[16:31], v[172:175], v[140:143], v[16:31]
	v_mfma_f32_32x32x16_bf16 v[0:15], v[176:179], v[140:143], v[0:15]
	s_nop 7
	s_nop 3
	s_barrier
	s_load_dwordx2 s[64:65], s[92:93], 0x150
	v_and_b32_e32 v160, 31, v196
	v_bfe_u32 v162, v196, 5, 1
	s_lshr_b32 s74, s73, 1
	s_lshl_b32 s74, s74, 6
	s_add_u32 s74, s74, s77
	v_add_u32_e32 v163, s74, v160
	s_mul_i32 s76, s73, 8704
	v_mul_u32_u24_e32 v181, 272, v160
	v_lshl_add_u32 v181, v162, 3, v181
	v_add_u32_e32 v181, s76, v181
	v_bfe_u32 v186, v196, 4, 2
	v_and_b32_e32 v187, 15, v196
	v_mul_u32_u24_e32 v182, 272, v186
	v_lshl_add_u32 v182, v187, 4, v182
	v_add_u32_e32 v182, s76, v182
	s_and_b32 s75, s73, 1
	s_lshl_b32 s75, s75, 7
	s_add_u32 s75, s75, s78
	v_add_u32_e32 v180, s74, v186
	v_mul_u32_u24_e32 v180, 0xe00, v180
	v_lshl_add_u32 v180, v187, 3, v180
	v_add_lshl_u32 v183, v180, s75, 1
	s_waitcnt lgkmcnt(0)
	v_cvt_pk_bf16_f32 v112, v112, v113
	v_cvt_pk_bf16_f32 v113, v114, v115
	ds_write_b64 v181, v[112:113]
	v_cvt_pk_bf16_f32 v116, v116, v117
	v_cvt_pk_bf16_f32 v117, v118, v119
	ds_write_b64 v181, v[116:117] offset:16
	v_cvt_pk_bf16_f32 v120, v120, v121
	v_cvt_pk_bf16_f32 v121, v122, v123
	ds_write_b64 v181, v[120:121] offset:32
	v_cvt_pk_bf16_f32 v124, v124, v125
	v_cvt_pk_bf16_f32 v125, v126, v127
	ds_write_b64 v181, v[124:125] offset:48
	v_cvt_pk_bf16_f32 v96, v96, v97
	v_cvt_pk_bf16_f32 v97, v98, v99
	ds_write_b64 v181, v[96:97] offset:64
	v_cvt_pk_bf16_f32 v100, v100, v101
	v_cvt_pk_bf16_f32 v101, v102, v103
	ds_write_b64 v181, v[100:101] offset:80
	v_cvt_pk_bf16_f32 v104, v104, v105
	v_cvt_pk_bf16_f32 v105, v106, v107
	ds_write_b64 v181, v[104:105] offset:96
	v_cvt_pk_bf16_f32 v108, v108, v109
	v_cvt_pk_bf16_f32 v109, v110, v111
	ds_write_b64 v181, v[108:109] offset:112
	v_cvt_pk_bf16_f32 v80, v80, v81
	v_cvt_pk_bf16_f32 v81, v82, v83
	ds_write_b64 v181, v[80:81] offset:128
	v_cvt_pk_bf16_f32 v84, v84, v85
	v_cvt_pk_bf16_f32 v85, v86, v87
	ds_write_b64 v181, v[84:85] offset:144
	v_cvt_pk_bf16_f32 v88, v88, v89
	v_cvt_pk_bf16_f32 v89, v90, v91
	ds_write_b64 v181, v[88:89] offset:160
	v_cvt_pk_bf16_f32 v92, v92, v93
	v_cvt_pk_bf16_f32 v93, v94, v95
	ds_write_b64 v181, v[92:93] offset:176
	v_cvt_pk_bf16_f32 v64, v64, v65
	v_cvt_pk_bf16_f32 v65, v66, v67
	ds_write_b64 v181, v[64:65] offset:192
	v_cvt_pk_bf16_f32 v68, v68, v69
	v_cvt_pk_bf16_f32 v69, v70, v71
	ds_write_b64 v181, v[68:69] offset:208
	v_cvt_pk_bf16_f32 v72, v72, v73
	v_cvt_pk_bf16_f32 v73, v74, v75
	ds_write_b64 v181, v[72:73] offset:224
	v_cvt_pk_bf16_f32 v76, v76, v77
	v_cvt_pk_bf16_f32 v77, v78, v79
	ds_write_b64 v181, v[76:77] offset:240
	s_waitcnt lgkmcnt(0)
; DI bfr f2bf(float a) { return (bfr)(pack2(a, 0.f) & 0xffffu); }
; DI int crow(int reg, int h) { return (reg & 3) + 8 * (reg >> 2) + 4 * h; }
; template <int lda, class Epi>
; DI void gemm_tile(const bfr* __restrict__ A, const bfr* __restrict__ Bt, int NB, int K, int m0, int n0, char* smem, Epi epi) {
;     ...
;   const int lane = tid3 & 63, wid = tid3 >> 6, wr = wid >> 1, wc = wid & 1, r = lane & 31, hl = lane >> 5;
; #pragma unroll
;   for (int i = 0; i < 2; ++i)
; #pragma unroll
;     for (int j = 0; j < 4; ++j)
; #pragma unroll
;       for (int q = 0; q < 16; ++q) {
;         int row = m0 + wr * 64 + i * 32 + crow(q, hl);
;         int col = n0 + wc * 128 + j * 32 + r;
;         epi(row, col, acc[i][j][q]);
;       }
; DI void phase_gemm_in_even(const Params& p, char* smem) {
;     ...
;                 [=](int row, int col, float v) { PB[(size_t)row * EINP + col] = f2bf(v); });
	ds_read_b128 v[112:115], v182
	ds_read_b128 v[116:119], v182 offset:1088
	ds_read_b128 v[120:123], v182 offset:2176
	ds_read_b128 v[124:127], v182 offset:3264
	ds_read_b128 v[96:99], v182 offset:4352
	ds_read_b128 v[100:103], v182 offset:5440
	ds_read_b128 v[104:107], v182 offset:6528
	ds_read_b128 v[108:111], v182 offset:7616
	s_add_u32 s66, s64, 0x0
	s_addc_u32 s67, s65, 0
	s_waitcnt lgkmcnt(7)
	global_store_dwordx4 v183, v[112:115], s[66:67]
	s_add_u32 s66, s64, 0x7000
	s_addc_u32 s67, s65, 0
	s_waitcnt lgkmcnt(6)
	global_store_dwordx4 v183, v[116:119], s[66:67]
	s_add_u32 s66, s64, 0xe000
	s_addc_u32 s67, s65, 0
	s_waitcnt lgkmcnt(5)
	global_store_dwordx4 v183, v[120:123], s[66:67]
	s_add_u32 s66, s64, 0x15000
	s_addc_u32 s67, s65, 0
	s_waitcnt lgkmcnt(4)
	global_store_dwordx4 v183, v[124:127], s[66:67]
	s_add_u32 s66, s64, 0x1c000
	s_addc_u32 s67, s65, 0
	s_waitcnt lgkmcnt(3)
	global_store_dwordx4 v183, v[96:99], s[66:67]
	s_add_u32 s66, s64, 0x23000
	s_addc_u32 s67, s65, 0
	s_waitcnt lgkmcnt(2)
	global_store_dwordx4 v183, v[100:103], s[66:67]
	s_add_u32 s66, s64, 0x2a000
	s_addc_u32 s67, s65, 0
	s_waitcnt lgkmcnt(1)
	global_store_dwordx4 v183, v[104:107], s[66:67]
	s_add_u32 s66, s64, 0x31000
	s_addc_u32 s67, s65, 0
	s_waitcnt lgkmcnt(0)
	global_store_dwordx4 v183, v[108:111], s[66:67]
	v_cvt_pk_bf16_f32 v48, v48, v49
	v_cvt_pk_bf16_f32 v49, v50, v51
	ds_write_b64 v181, v[48:49]
	v_cvt_pk_bf16_f32 v52, v52, v53
	v_cvt_pk_bf16_f32 v53, v54, v55
	ds_write_b64 v181, v[52:53] offset:16
	v_cvt_pk_bf16_f32 v56, v56, v57
	v_cvt_pk_bf16_f32 v57, v58, v59
	ds_write_b64 v181, v[56:57] offset:32
	v_cvt_pk_bf16_f32 v60, v60, v61
	v_cvt_pk_bf16_f32 v61, v62, v63
	ds_write_b64 v181, v[60:61] offset:48
	v_cvt_pk_bf16_f32 v32, v32, v33
	v_cvt_pk_bf16_f32 v33, v34, v35
	ds_write_b64 v181, v[32:33] offset:64
	v_cvt_pk_bf16_f32 v36, v36, v37
	v_cvt_pk_bf16_f32 v37, v38, v39
	ds_write_b64 v181, v[36:37] offset:80
	v_cvt_pk_bf16_f32 v40, v40, v41
	v_cvt_pk_bf16_f32 v41, v42, v43
	ds_write_b64 v181, v[40:41] offset:96
	v_cvt_pk_bf16_f32 v44, v44, v45
	v_cvt_pk_bf16_f32 v45, v46, v47
	ds_write_b64 v181, v[44:45] offset:112
	v_cvt_pk_bf16_f32 v16, v16, v17
	v_cvt_pk_bf16_f32 v17, v18, v19
	ds_write_b64 v181, v[16:17] offset:128
	v_cvt_pk_bf16_f32 v20, v20, v21
	v_cvt_pk_bf16_f32 v21, v22, v23
	ds_write_b64 v181, v[20:21] offset:144
	v_cvt_pk_bf16_f32 v24, v24, v25
	v_cvt_pk_bf16_f32 v25, v26, v27
	ds_write_b64 v181, v[24:25] offset:160
	v_cvt_pk_bf16_f32 v28, v28, v29
	v_cvt_pk_bf16_f32 v29, v30, v31
	ds_write_b64 v181, v[28:29] offset:176
	v_cvt_pk_bf16_f32 v0, v0, v1
	v_cvt_pk_bf16_f32 v1, v2, v3
	ds_write_b64 v181, v[0:1] offset:192
	v_cvt_pk_bf16_f32 v4, v4, v5
	v_cvt_pk_bf16_f32 v5, v6, v7
	ds_write_b64 v181, v[4:5] offset:208
	v_cvt_pk_bf16_f32 v8, v8, v9
	v_cvt_pk_bf16_f32 v9, v10, v11
	ds_write_b64 v181, v[8:9] offset:224
	v_cvt_pk_bf16_f32 v12, v12, v13
	v_cvt_pk_bf16_f32 v13, v14, v15
	ds_write_b64 v181, v[12:13] offset:240
	s_waitcnt lgkmcnt(0)
	ds_read_b128 v[48:51], v182
	ds_read_b128 v[52:55], v182 offset:1088
	ds_read_b128 v[56:59], v182 offset:2176
	ds_read_b128 v[60:63], v182 offset:3264
	ds_read_b128 v[32:35], v182 offset:4352
	ds_read_b128 v[36:39], v182 offset:5440
	ds_read_b128 v[40:43], v182 offset:6528
	ds_read_b128 v[44:47], v182 offset:7616
	s_add_u32 s66, s64, 0x38000
	s_addc_u32 s67, s65, 0
	s_waitcnt lgkmcnt(7)
	global_store_dwordx4 v183, v[48:51], s[66:67]
	s_add_u32 s66, s64, 0x3f000
	s_addc_u32 s67, s65, 0
	s_waitcnt lgkmcnt(6)
	global_store_dwordx4 v183, v[52:55], s[66:67]
	s_add_u32 s66, s64, 0x46000
	s_addc_u32 s67, s65, 0
	s_waitcnt lgkmcnt(5)
	global_store_dwordx4 v183, v[56:59], s[66:67]
	s_add_u32 s66, s64, 0x4d000
	s_addc_u32 s67, s65, 0
	s_waitcnt lgkmcnt(4)
	global_store_dwordx4 v183, v[60:63], s[66:67]
	s_add_u32 s66, s64, 0x54000
	s_addc_u32 s67, s65, 0
	s_waitcnt lgkmcnt(3)
	global_store_dwordx4 v183, v[32:35], s[66:67]
	s_add_u32 s66, s64, 0x5b000
	s_addc_u32 s67, s65, 0
	s_waitcnt lgkmcnt(2)
	global_store_dwordx4 v183, v[36:39], s[66:67]
	s_add_u32 s66, s64, 0x62000
	s_addc_u32 s67, s65, 0
	s_waitcnt lgkmcnt(1)
	global_store_dwordx4 v183, v[40:43], s[66:67]
	s_add_u32 s66, s64, 0x69000
	s_addc_u32 s67, s65, 0
	s_waitcnt lgkmcnt(0)
	global_store_dwordx4 v183, v[44:47], s[66:67]
	v_readlane_b32 s64, v188, 0
	v_readlane_b32 s65, v188, 1
	v_readlane_b32 s66, v188, 2
	v_readlane_b32 s67, v188, 3
	v_readlane_b32 s68, v188, 4
	v_readlane_b32 s69, v188, 5
	v_readlane_b32 s70, v188, 6
	v_readlane_b32 s71, v188, 7
	v_readlane_b32 s72, v188, 8
	v_readlane_b32 s73, v188, 9
	v_readlane_b32 s74, v188, 10
	v_readlane_b32 s75, v188, 11
	v_readlane_b32 s76, v188, 12
	v_readlane_b32 s77, v188, 13
	v_readlane_b32 s78, v188, 14
	v_readlane_b32 s79, v188, 15
	s_nop 7
	s_branch .LBB0_119

; #define GA_LOAD(pr_) do { _Pragma("unroll") for (int i = 0; i < 4; ++i) ra[i] = *(const u32x4*)(Ab + (i * 32) * lda + (pr_) * 64); } while (0)
; #define GB_LOAD(kt_) do { const bfr* bk_ = Bb + (kt_) * NB * 32; \
;     _Pragma("unroll") for (int i = 0; i < 4; ++i) rb[i] = *(const u32x4*)(bk_ + (i * 64) * 32); } while (0)
; #define G_STORE(kt_) do { bfr* as_ = S0 + ((kt_) & 1) * GSTAGE; bfr* bs_ = as_ + 128 * 40; \
;     if (apar == ((kt_) & 1)) { _Pragma("unroll") for (int i = 0; i < 4; ++i) *(u32x4*)(as_ + asoff + i * 32 * 40) = ra[i]; } \
;     _Pragma("unroll") for (int i = 0; i < 4; ++i) *(u32x4*)(bs_ + bsoff + i * 64 * 40) = rb[i]; } while (0)
; template <int lda>
; DI void gemm_mainloop(const bfr* __restrict__ A, const bfr* __restrict__ Bt, int NB, int K, int m0, int n0, char* smem, f32x16 (&acc)[2][4]) {
;     ...
;   const int nk = K >> 5;
;   const int arow = tid >> 3, ac8 = tid & 7, apar = ac8 >> 2;
;   const bfr* Ab = A + (m0 + arow) * lda + ac8 * 8;
;   const int asoff = arow * 40 + (ac8 & 3) * 8;
;   const int brow = tid >> 2, bc4 = tid & 3;
;   const bfr* Bb = Bt + (n0 + brow) * 32 + bc4 * 8;
;   const int bsoff = brow * 40 + bc4 * 8;
;     ...
;   GA_LOAD(0);
;   GB_LOAD(0);
;   G_STORE(0);
;   GB_LOAD(1);
;   __syncthreads();
; DI void phase_gemm_bf16out(const Params& p, const bfr* A, const bfr* Wt, bfr* C, int N, const float* ss, char* smem) {
;     ...
;   for (int t0 = blockIdx.x; t0 < 128 * ntn; t0 += gridDim.x) {
;     const int t = ((gridDim.x & 7) == 0) ? xcd_tile(t0, ntn) : t0;
;     int mt = t / ntn, nt = t % ntn;
;     gemm_tile<1024>(A, Wt, N, 1024, mt * 128, nt * 256, smem,
.LBB0_925:
	s_ashr_i32 s5, s4, 31
	s_lshr_b32 s5, s5, 30
	s_add_i32 s5, s4, s5
	s_and_b32 s6, s5, 0xfffffc
	s_lshl_b32 s5, s5, 5
	s_and_b32 s30, s5, 0xffffff80
	s_sub_i32 s4, s4, s6
	s_lshl_b32 s29, s4, 8
	s_mov_b32 s31, 0
	s_mov_b64 s[6:7], 0
	s_lshl_b32 s98, s30, 11
	s_add_u32 s98, s10, s98
	s_addc_u32 s99, s11, 0
	s_lshl_b32 s100, s29, 6
	s_add_u32 s100, s12, s100
	s_addc_u32 s101, s13, 0
	v_writelane_b32 v187, s64, 0
	v_writelane_b32 v187, s65, 1
	v_writelane_b32 v187, s66, 2
	v_writelane_b32 v187, s67, 3
	v_writelane_b32 v187, s68, 4
	v_writelane_b32 v187, s69, 5
	v_writelane_b32 v187, s70, 6
	v_writelane_b32 v187, s71, 7
	v_writelane_b32 v187, s72, 8
	v_writelane_b32 v187, s73, 9
	v_writelane_b32 v187, s74, 10
	v_writelane_b32 v187, s75, 11
	v_writelane_b32 v187, s76, 12
	v_writelane_b32 v187, s77, 13
	v_writelane_b32 v187, s78, 14
	v_writelane_b32 v187, s79, 15
	s_mov_b32 s77, s30
	s_mov_b32 s78, s29
	v_lshrrev_b32_e32 v188, 6, v196
	v_and_b32_e32 v189, 63, v196
	v_readfirstlane_b32 s73, v188
	v_lshrrev_b32_e32 v190, 2, v189
	v_bfe_u32 v191, v189, 4, 2
	v_and_b32_e32 v188, 3, v189
	v_xor_b32_e32 v188, v188, v191
	v_lshlrev_b32_e32 v188, 4, v188
	v_lshl_add_u32 v176, v190, 11, v188
	v_add_u32_e32 v177, 0x8000, v176
	v_lshl_add_u32 v178, v190, 6, v188
	v_and_b32_e32 v190, 31, v189
	v_lshrrev_b32_e32 v191, 5, v189
	v_bfe_u32 v188, v189, 2, 2
	v_xor_b32_e32 v188, v188, v191
	v_lshlrev_b32_e32 v188, 4, v188
	v_lshl_add_u32 v179, v190, 6, v188
	s_lshr_b32 s74, s73, 1
	s_lshl_b32 s74, s74, 12
	s_and_b32 s75, s73, 1
	s_lshl_b32 s75, s75, 13
	v_add_u32_e32 v181, s75, v179
	v_add_u32_e32 v179, s74, v179
	v_xor_b32_e32 v182, 32, v181
	v_xor_b32_e32 v180, 32, v179
	s_lshl_b32 s74, s73, 16
	s_add_u32 s64, s98, s74
	s_addc_u32 s65, s99, 0
	s_lshl_b32 s74, s73, 12
	s_add_u32 s66, s100, s74
	s_addc_u32 s67, s101, 0
	s_lshl_b32 s68, s73, 11
	s_lshl_b32 s69, s73, 12
	s_mov_b32 s70, 0
	s_mov_b32 s71, 0
	s_mov_b32 s72, 0
	s_waitcnt lgkmcnt(0)
	s_barrier
	s_mul_i32 s74, s70, 0x6000
	s_add_u32 s75, s74, s68
	s_mov_b32 m0, s75
	s_add_u32 s76, s74, 0x2000
	s_cmp_eq_u32 s70, 2
	s_cselect_b32 s76, 0x10000, s76
	global_load_lds_dwordx4 v176, s[64:65]
	s_add_u32 m0, s75, 0x400
	s_add_u32 s76, s76, s69
	global_load_lds_dwordx4 v177, s[64:65]
	s_mov_b32 m0, s76
	s_add_u32 s64, s64, 64
	s_addc_u32 s65, s65, 0
	global_load_lds_dwordx4 v178, s[66:67]
	global_load_lds_dwordx4 v178, s[66:67] offset:1024
	global_load_lds_dwordx4 v178, s[66:67] offset:2048
	global_load_lds_dwordx4 v178, s[66:67] offset:3072
	s_add_u32 s66, s66, 0x10000
	s_addc_u32 s67, s67, 0
	s_add_u32 s70, s70, 1
	s_cmp_eq_u32 s70, 3
	s_cselect_b32 s70, 0, s70
	s_mul_i32 s74, s70, 0x6000
	s_add_u32 s75, s74, s68
	s_mov_b32 m0, s75
	s_add_u32 s76, s74, 0x2000
	s_cmp_eq_u32 s70, 2
	s_cselect_b32 s76, 0x10000, s76
	global_load_lds_dwordx4 v176, s[64:65]
	s_add_u32 m0, s75, 0x400
	s_add_u32 s76, s76, s69
	global_load_lds_dwordx4 v177, s[64:65]
	s_mov_b32 m0, s76
	s_add_u32 s64, s64, 64
	s_addc_u32 s65, s65, 0
	global_load_lds_dwordx4 v178, s[66:67]
	global_load_lds_dwordx4 v178, s[66:67] offset:1024
	global_load_lds_dwordx4 v178, s[66:67] offset:2048
	global_load_lds_dwordx4 v178, s[66:67] offset:3072
	s_add_u32 s66, s66, 0x10000
	s_addc_u32 s67, s67, 0
	s_add_u32 s70, s70, 1
	s_cmp_eq_u32 s70, 3
	s_cselect_b32 s70, 0, s70
	s_cmp_lt_u32 s46, 0x100
	s_cbranch_scc1 .Lp8_nostag
	s_sleep 8

; #define MFMA32(a, b, c) __builtin_amdgcn_mfma_f32_32x32x16_bf16((a), (b), (c), 0, 0, 0)
; #define GA_LOAD(pr_) do { _Pragma("unroll") for (int i = 0; i < 4; ++i) ra[i] = *(const u32x4*)(Ab + (i * 32) * lda + (pr_) * 64); } while (0)
; #define GB_LOAD(kt_) do { const bfr* bk_ = Bb + (kt_) * NB * 32; \
;     _Pragma("unroll") for (int i = 0; i < 4; ++i) rb[i] = *(const u32x4*)(bk_ + (i * 64) * 32); } while (0)
; #define G_STORE(kt_) do { bfr* as_ = S0 + ((kt_) & 1) * GSTAGE; bfr* bs_ = as_ + 128 * 40; \
;     if (apar == ((kt_) & 1)) { _Pragma("unroll") for (int i = 0; i < 4; ++i) *(u32x4*)(as_ + asoff + i * 32 * 40) = ra[i]; } \
;     _Pragma("unroll") for (int i = 0; i < 4; ++i) *(u32x4*)(bs_ + bsoff + i * 64 * 40) = rb[i]; } while (0)
; template <int lda>
; DI void gemm_mainloop(const bfr* __restrict__ A, const bfr* __restrict__ Bt, int NB, int K, int m0, int n0, char* smem, f32x16 (&acc)[2][4]) {
;     ...
;   for (int kt = 0; kt < nk; ++kt) {
;     if (kt + 1 < nk) G_STORE(kt + 1);
;     if (kt + 2 < nk) {
;       GB_LOAD(kt + 2);
;       if ((kt & 1) == 0) GA_LOAD((kt >> 1) + 1);
;     }
;     const bfr* As = S0 + (kt & 1) * GSTAGE;
;     const bfr* Bs = As + 128 * 40;
; #pragma unroll
;     for (int ks = 0; ks < 2; ++ks) {
;       bf16x8 af[2], bfg[4];
; #pragma unroll
;       for (int i = 0; i < 2; ++i) af[i] = *(const bf16x8*)(As + (wr * 64 + i * 32 + r) * 40 + ks * 16 + hl * 8);
; #pragma unroll
;       for (int j = 0; j < 4; ++j) bfg[j] = *(const bf16x8*)(Bs + (wc * 128 + j * 32 + r) * 40 + ks * 16 + hl * 8);
; #pragma unroll
;       for (int i = 0; i < 2; ++i)
; #pragma unroll
;         for (int j = 0; j < 4; ++j) acc[i][j] = MFMA32(af[i], bfg[j], acc[i][j]);
;     }
;     __syncthreads();
;   }
.Lp8_loop:
	s_waitcnt vmcnt(6)
	s_barrier
	s_mul_i32 s74, s71, 0x6000
	s_add_u32 s75, s74, 0x2000
	s_cmp_eq_u32 s71, 2
	s_cselect_b32 s75, 0x10000, s75
	v_add_u32_e32 v183, s74, v179
	v_add_u32_e32 v185, s75, v181
	v_add_u32_e32 v184, s74, v180
	v_add_u32_e32 v186, s75, v182
	ds_read_b128 v[128:131], v183
	ds_read_b128 v[144:147], v185
	ds_read_b128 v[148:151], v185 offset:2048
	ds_read_b128 v[152:155], v185 offset:4096
	ds_read_b128 v[156:159], v185 offset:6144
	ds_read_b128 v[132:135], v183 offset:2048
	ds_read_b128 v[136:139], v184
	ds_read_b128 v[160:163], v186
	ds_read_b128 v[164:167], v186 offset:2048
	ds_read_b128 v[168:171], v186 offset:4096
	ds_read_b128 v[172:175], v186 offset:6144
	ds_read_b128 v[140:143], v184 offset:2048
	s_add_u32 s71, s71, 1
	s_cmp_eq_u32 s71, 3
	s_cselect_b32 s71, 0, s71
	s_waitcnt lgkmcnt(10)
	v_mfma_f32_32x32x16_bf16 v[112:127], v[144:147], v[128:131], v[112:127]
	s_mul_i32 s74, s70, 0x6000
	s_add_u32 s75, s74, s68
	s_mov_b32 m0, s75
	s_add_u32 s76, s74, 0x2000
	s_cmp_eq_u32 s70, 2
	s_cselect_b32 s76, 0x10000, s76
	global_load_lds_dwordx4 v176, s[64:65]
	s_waitcnt lgkmcnt(9)
	v_mfma_f32_32x32x16_bf16 v[96:111], v[148:151], v[128:131], v[96:111]
	s_add_u32 m0, s75, 0x400
	s_add_u32 s76, s76, s69
	global_load_lds_dwordx4 v177, s[64:65]
	s_waitcnt lgkmcnt(8)
	v_mfma_f32_32x32x16_bf16 v[80:95], v[152:155], v[128:131], v[80:95]
	s_mov_b32 m0, s76
	s_add_u32 s64, s64, 64
	s_addc_u32 s65, s65, 0
	global_load_lds_dwordx4 v178, s[66:67]
	s_waitcnt lgkmcnt(7)
	v_mfma_f32_32x32x16_bf16 v[64:79], v[156:159], v[128:131], v[64:79]
	global_load_lds_dwordx4 v178, s[66:67] offset:1024
	s_waitcnt lgkmcnt(6)
	v_mfma_f32_32x32x16_bf16 v[48:63], v[144:147], v[132:135], v[48:63]
	global_load_lds_dwordx4 v178, s[66:67] offset:2048
	v_mfma_f32_32x32x16_bf16 v[32:47], v[148:151], v[132:135], v[32:47]
	global_load_lds_dwordx4 v178, s[66:67] offset:3072
	s_add_u32 s66, s66, 0x10000
	s_addc_u32 s67, s67, 0
	v_mfma_f32_32x32x16_bf16 v[16:31], v[152:155], v[132:135], v[16:31]
	s_add_u32 s70, s70, 1
	s_cmp_eq_u32 s70, 3
	s_cselect_b32 s70, 0, s70
	v_mfma_f32_32x32x16_bf16 v[0:15], v[156:159], v[132:135], v[0:15]
	s_waitcnt lgkmcnt(4)
	v_mfma_f32_32x32x16_bf16 v[112:127], v[160:163], v[136:139], v[112:127]
	s_waitcnt lgkmcnt(3)
	v_mfma_f32_32x32x16_bf16 v[96:111], v[164:167], v[136:139], v[96:111]
	s_waitcnt lgkmcnt(2)
	v_mfma_f32_32x32x16_bf16 v[80:95], v[168:171], v[136:139], v[80:95]
	s_waitcnt lgkmcnt(1)
	v_mfma_f32_32x32x16_bf16 v[64:79], v[172:175], v[136:139], v[64:79]
	s_waitcnt lgkmcnt(0)
	v_mfma_f32_32x32x16_bf16 v[48:63], v[160:163], v[140:143], v[48:63]
	v_mfma_f32_32x32x16_bf16 v[32:47], v[164:167], v[140:143], v[32:47]
	v_mfma_f32_32x32x16_bf16 v[16:31], v[168:171], v[140:143], v[16:31]
	v_mfma_f32_32x32x16_bf16 v[0:15], v[172:175], v[140:143], v[0:15]
	s_add_u32 s72, s72, 1
	s_cmp_lt_u32 s72, 30
	s_cbranch_scc1 .Lp8_loop
	s_waitcnt vmcnt(6)
	s_barrier
	s_mul_i32 s74, s71, 0x6000
	s_add_u32 s75, s74, 0x2000
	s_cmp_eq_u32 s71, 2
	s_cselect_b32 s75, 0x10000, s75
	v_add_u32_e32 v183, s74, v179
	v_add_u32_e32 v185, s75, v181
	v_add_u32_e32 v184, s74, v180
	v_add_u32_e32 v186, s75, v182
	ds_read_b128 v[128:131], v183
	ds_read_b128 v[144:147], v185
	ds_read_b128 v[148:151], v185 offset:2048
	ds_read_b128 v[152:155], v185 offset:4096
	ds_read_b128 v[156:159], v185 offset:6144
	ds_read_b128 v[132:135], v183 offset:2048
	ds_read_b128 v[136:139], v184
	ds_read_b128 v[160:163], v186
	ds_read_b128 v[164:167], v186 offset:2048
	ds_read_b128 v[168:171], v186 offset:4096
	ds_read_b128 v[172:175], v186 offset:6144
	ds_read_b128 v[140:143], v184 offset:2048
	s_add_u32 s71, s71, 1
	s_cmp_eq_u32 s71, 3
	s_cselect_b32 s71, 0, s71
	s_waitcnt lgkmcnt(10)
	v_mfma_f32_32x32x16_bf16 v[112:127], v[144:147], v[128:131], v[112:127]
	s_waitcnt lgkmcnt(9)
	v_mfma_f32_32x32x16_bf16 v[96:111], v[148:151], v[128:131], v[96:111]
	s_waitcnt lgkmcnt(8)
	v_mfma_f32_32x32x16_bf16 v[80:95], v[152:155], v[128:131], v[80:95]
	s_waitcnt lgkmcnt(7)
	v_mfma_f32_32x32x16_bf16 v[64:79], v[156:159], v[128:131], v[64:79]
	s_waitcnt lgkmcnt(6)
	v_mfma_f32_32x32x16_bf16 v[48:63], v[144:147], v[132:135], v[48:63]
	v_mfma_f32_32x32x16_bf16 v[32:47], v[148:151], v[132:135], v[32:47]
	v_mfma_f32_32x32x16_bf16 v[16:31], v[152:155], v[132:135], v[16:31]
	v_mfma_f32_32x32x16_bf16 v[0:15], v[156:159], v[132:135], v[0:15]
	s_waitcnt lgkmcnt(4)
	v_mfma_f32_32x32x16_bf16 v[112:127], v[160:163], v[136:139], v[112:127]
	s_waitcnt lgkmcnt(3)
	v_mfma_f32_32x32x16_bf16 v[96:111], v[164:167], v[136:139], v[96:111]
	s_waitcnt lgkmcnt(2)
	v_mfma_f32_32x32x16_bf16 v[80:95], v[168:171], v[136:139], v[80:95]
	s_waitcnt lgkmcnt(1)
	v_mfma_f32_32x32x16_bf16 v[64:79], v[172:175], v[136:139], v[64:79]
	s_waitcnt lgkmcnt(0)
	v_mfma_f32_32x32x16_bf16 v[48:63], v[160:163], v[140:143], v[48:63]
	v_mfma_f32_32x32x16_bf16 v[32:47], v[164:167], v[140:143], v[32:47]
	v_mfma_f32_32x32x16_bf16 v[16:31], v[168:171], v[140:143], v[16:31]
	v_mfma_f32_32x32x16_bf16 v[0:15], v[172:175], v[140:143], v[0:15]
	s_waitcnt vmcnt(0)
	s_barrier
; DI bfr f2bf(float a) { return (bfr)(pack2(a, 0.f) & 0xffffu); }
; DI int crow(int reg, int h) { return (reg & 3) + 8 * (reg >> 2) + 4 * h; }
; template <int lda, class Epi>
; DI void gemm_tile(const bfr* __restrict__ A, const bfr* __restrict__ Bt, int NB, int K, int m0, int n0, char* smem, Epi epi) {
;     ...
;   const int lane = tid3 & 63, wid = tid3 >> 6, wr = wid >> 1, wc = wid & 1, r = lane & 31, hl = lane >> 5;
; #pragma unroll
;   for (int i = 0; i < 2; ++i)
; #pragma unroll
;     for (int j = 0; j < 4; ++j)
; #pragma unroll
;       for (int q = 0; q < 16; ++q) {
;         int row = m0 + wr * 64 + i * 32 + crow(q, hl);
;         int col = n0 + wc * 128 + j * 32 + r;
;         epi(row, col, acc[i][j][q]);
;       }
; DI void phase_gemm_bf16out(const Params& p, const bfr* A, const bfr* Wt, bfr* C, int N, const float* ss, char* smem) {
;     ...
;     gemm_tile<1024>(A, Wt, N, 1024, mt * 128, nt * 256, smem,
;               [=](int row, int col, float v) {
;                 float inv = rsqrtf(ss[row] * (1.0f / 1024.0f) + EPSF);
;                 C[(size_t)row * N + col] = f2bf(v * inv);
	s_mul_i32 s74, s71, 0x6000
	s_add_u32 s75, s74, 0x2000
	s_cmp_eq_u32 s71, 2
	s_cselect_b32 s75, 0x10000, s75
	v_add_u32_e32 v183, s74, v179
	v_add_u32_e32 v185, s75, v181
	v_add_u32_e32 v184, s74, v180
	v_add_u32_e32 v186, s75, v182
	ds_read_b128 v[128:131], v183
	ds_read_b128 v[144:147], v185
	ds_read_b128 v[148:151], v185 offset:2048
	ds_read_b128 v[152:155], v185 offset:4096
	ds_read_b128 v[156:159], v185 offset:6144
	ds_read_b128 v[132:135], v183 offset:2048
	ds_read_b128 v[136:139], v184
	ds_read_b128 v[160:163], v186
	ds_read_b128 v[164:167], v186 offset:2048
	ds_read_b128 v[168:171], v186 offset:4096
	ds_read_b128 v[172:175], v186 offset:6144
	ds_read_b128 v[140:143], v184 offset:2048
	s_add_u32 s71, s71, 1
	s_cmp_eq_u32 s71, 3
	s_cselect_b32 s71, 0, s71
	s_waitcnt lgkmcnt(10)
	v_mfma_f32_32x32x16_bf16 v[112:127], v[144:147], v[128:131], v[112:127]
	s_waitcnt lgkmcnt(9)
	v_mfma_f32_32x32x16_bf16 v[96:111], v[148:151], v[128:131], v[96:111]
	s_waitcnt lgkmcnt(8)
	v_mfma_f32_32x32x16_bf16 v[80:95], v[152:155], v[128:131], v[80:95]
	s_waitcnt lgkmcnt(7)
	v_mfma_f32_32x32x16_bf16 v[64:79], v[156:159], v[128:131], v[64:79]
	s_waitcnt lgkmcnt(6)
	v_mfma_f32_32x32x16_bf16 v[48:63], v[144:147], v[132:135], v[48:63]
	v_mfma_f32_32x32x16_bf16 v[32:47], v[148:151], v[132:135], v[32:47]
	v_mfma_f32_32x32x16_bf16 v[16:31], v[152:155], v[132:135], v[16:31]
	v_mfma_f32_32x32x16_bf16 v[0:15], v[156:159], v[132:135], v[0:15]
	s_waitcnt lgkmcnt(4)
	v_mfma_f32_32x32x16_bf16 v[112:127], v[160:163], v[136:139], v[112:127]
	s_waitcnt lgkmcnt(3)
	v_mfma_f32_32x32x16_bf16 v[96:111], v[164:167], v[136:139], v[96:111]
	s_waitcnt lgkmcnt(2)
	v_mfma_f32_32x32x16_bf16 v[80:95], v[168:171], v[136:139], v[80:95]
	s_waitcnt lgkmcnt(1)
	v_mfma_f32_32x32x16_bf16 v[64:79], v[172:175], v[136:139], v[64:79]
	s_waitcnt lgkmcnt(0)
	v_mfma_f32_32x32x16_bf16 v[48:63], v[160:163], v[140:143], v[48:63]
	v_mfma_f32_32x32x16_bf16 v[32:47], v[164:167], v[140:143], v[32:47]
	v_mfma_f32_32x32x16_bf16 v[16:31], v[168:171], v[140:143], v[16:31]
	v_mfma_f32_32x32x16_bf16 v[0:15], v[172:175], v[140:143], v[0:15]
	s_nop 7
	s_nop 3
	s_barrier
	s_load_dwordx2 s[64:65], s[92:93], 0x160
	s_load_dwordx2 s[66:67], s[92:93], 0x140
	v_and_b32_e32 v176, 31, v196
	v_bfe_u32 v177, v196, 5, 1
	s_lshr_b32 s74, s73, 1
	s_lshl_b32 s74, s74, 6
	s_add_u32 s74, s74, s77
	v_add_u32_e32 v178, s74, v176
	s_mul_i32 s76, s73, 8704
	v_mul_u32_u24_e32 v180, 272, v176
	v_lshl_add_u32 v180, v177, 3, v180
	v_add_u32_e32 v180, s76, v180
	v_bfe_u32 v185, v196, 4, 2
	v_and_b32_e32 v186, 15, v196
	v_mul_u32_u24_e32 v181, 272, v185
	v_lshl_add_u32 v181, v186, 4, v181
	v_add_u32_e32 v181, s76, v181
	s_and_b32 s75, s73, 1
	s_lshl_b32 s75, s75, 7
	s_add_u32 s75, s75, s78
	v_add_u32_e32 v179, s74, v185
	v_mul_u32_u24_e32 v179, 0x400, v179
	v_lshl_add_u32 v179, v186, 3, v179
	v_add_lshl_u32 v182, v179, s75, 1
	s_waitcnt lgkmcnt(0)
	v_lshlrev_b32_e32 v179, 2, v178
	global_load_dword v183, v179, s[66:67]
	global_load_dword v184, v179, s[66:67] offset:128
	s_waitcnt vmcnt(0)
	v_mul_f32_e32 v183, 0x3a800000, v183
	v_mul_f32_e32 v184, 0x3a800000, v184
	v_add_f32_e32 v183, 0x358637bd, v183
	v_add_f32_e32 v184, 0x358637bd, v184
	v_rsq_f32_e32 v183, v183
	v_rsq_f32_e32 v184, v184
	s_nop 1
	v_mul_f32_e32 v112, v183, v112
	v_mul_f32_e32 v113, v183, v113
	v_mul_f32_e32 v114, v183, v114
	v_mul_f32_e32 v115, v183, v115
	v_cvt_pk_bf16_f32 v112, v112, v113
	v_cvt_pk_bf16_f32 v113, v114, v115
	ds_write_b64 v180, v[112:113]
	v_mul_f32_e32 v116, v183, v116
	v_mul_f32_e32 v117, v183, v117
	v_mul_f32_e32 v118, v183, v118
	v_mul_f32_e32 v119, v183, v119
	v_cvt_pk_bf16_f32 v116, v116, v117
	v_cvt_pk_bf16_f32 v117, v118, v119
	ds_write_b64 v180, v[116:117] offset:16
	v_mul_f32_e32 v120, v183, v120
	v_mul_f32_e32 v121, v183, v121
	v_mul_f32_e32 v122, v183, v122
	v_mul_f32_e32 v123, v183, v123
	v_cvt_pk_bf16_f32 v120, v120, v121
	v_cvt_pk_bf16_f32 v121, v122, v123
	ds_write_b64 v180, v[120:121] offset:32
	v_mul_f32_e32 v124, v183, v124
	v_mul_f32_e32 v125, v183, v125
	v_mul_f32_e32 v126, v183, v126
	v_mul_f32_e32 v127, v183, v127
	v_cvt_pk_bf16_f32 v124, v124, v125
	v_cvt_pk_bf16_f32 v125, v126, v127
	ds_write_b64 v180, v[124:125] offset:48
	v_mul_f32_e32 v96, v183, v96
	v_mul_f32_e32 v97, v183, v97
	v_mul_f32_e32 v98, v183, v98
	v_mul_f32_e32 v99, v183, v99
	v_cvt_pk_bf16_f32 v96, v96, v97
	v_cvt_pk_bf16_f32 v97, v98, v99
	ds_write_b64 v180, v[96:97] offset:64
	v_mul_f32_e32 v100, v183, v100
	v_mul_f32_e32 v101, v183, v101
	v_mul_f32_e32 v102, v183, v102
	v_mul_f32_e32 v103, v183, v103
	v_cvt_pk_bf16_f32 v100, v100, v101
	v_cvt_pk_bf16_f32 v101, v102, v103
	ds_write_b64 v180, v[100:101] offset:80
	v_mul_f32_e32 v104, v183, v104
	v_mul_f32_e32 v105, v183, v105
	v_mul_f32_e32 v106, v183, v106
	v_mul_f32_e32 v107, v183, v107
	v_cvt_pk_bf16_f32 v104, v104, v105
	v_cvt_pk_bf16_f32 v105, v106, v107
	ds_write_b64 v180, v[104:105] offset:96
	v_mul_f32_e32 v108, v183, v108
	v_mul_f32_e32 v109, v183, v109
	v_mul_f32_e32 v110, v183, v110
	v_mul_f32_e32 v111, v183, v111
	v_cvt_pk_bf16_f32 v108, v108, v109
	v_cvt_pk_bf16_f32 v109, v110, v111
	ds_write_b64 v180, v[108:109] offset:112
	v_mul_f32_e32 v80, v183, v80
	v_mul_f32_e32 v81, v183, v81
	v_mul_f32_e32 v82, v183, v82
	v_mul_f32_e32 v83, v183, v83
	v_cvt_pk_bf16_f32 v80, v80, v81
	v_cvt_pk_bf16_f32 v81, v82, v83
	ds_write_b64 v180, v[80:81] offset:128
	v_mul_f32_e32 v84, v183, v84
	v_mul_f32_e32 v85, v183, v85
	v_mul_f32_e32 v86, v183, v86
	v_mul_f32_e32 v87, v183, v87
	v_cvt_pk_bf16_f32 v84, v84, v85
	v_cvt_pk_bf16_f32 v85, v86, v87
	ds_write_b64 v180, v[84:85] offset:144
	v_mul_f32_e32 v88, v183, v88
	v_mul_f32_e32 v89, v183, v89
	v_mul_f32_e32 v90, v183, v90
	v_mul_f32_e32 v91, v183, v91
	v_cvt_pk_bf16_f32 v88, v88, v89
	v_cvt_pk_bf16_f32 v89, v90, v91
	ds_write_b64 v180, v[88:89] offset:160
	v_mul_f32_e32 v92, v183, v92
	v_mul_f32_e32 v93, v183, v93
	v_mul_f32_e32 v94, v183, v94
	v_mul_f32_e32 v95, v183, v95
	v_cvt_pk_bf16_f32 v92, v92, v93
	v_cvt_pk_bf16_f32 v93, v94, v95
	ds_write_b64 v180, v[92:93] offset:176
	v_mul_f32_e32 v64, v183, v64
	v_mul_f32_e32 v65, v183, v65
	v_mul_f32_e32 v66, v183, v66
	v_mul_f32_e32 v67, v183, v67
	v_cvt_pk_bf16_f32 v64, v64, v65
	v_cvt_pk_bf16_f32 v65, v66, v67
	ds_write_b64 v180, v[64:65] offset:192
	v_mul_f32_e32 v68, v183, v68
	v_mul_f32_e32 v69, v183, v69
	v_mul_f32_e32 v70, v183, v70
	v_mul_f32_e32 v71, v183, v71
	v_cvt_pk_bf16_f32 v68, v68, v69
	v_cvt_pk_bf16_f32 v69, v70, v71
	ds_write_b64 v180, v[68:69] offset:208
	v_mul_f32_e32 v72, v183, v72
	v_mul_f32_e32 v73, v183, v73
	v_mul_f32_e32 v74, v183, v74
	v_mul_f32_e32 v75, v183, v75
	v_cvt_pk_bf16_f32 v72, v72, v73
	v_cvt_pk_bf16_f32 v73, v74, v75
	ds_write_b64 v180, v[72:73] offset:224
	v_mul_f32_e32 v76, v183, v76
	v_mul_f32_e32 v77, v183, v77
	v_mul_f32_e32 v78, v183, v78
	v_mul_f32_e32 v79, v183, v79
	v_cvt_pk_bf16_f32 v76, v76, v77
	v_cvt_pk_bf16_f32 v77, v78, v79
	ds_write_b64 v180, v[76:77] offset:240
	s_waitcnt lgkmcnt(0)
; DI bfr f2bf(float a) { return (bfr)(pack2(a, 0.f) & 0xffffu); }
; DI void phase_gemm_bf16out(const Params& p, const bfr* A, const bfr* Wt, bfr* C, int N, const float* ss, char* smem) {
;     ...
;   for (int t0 = blockIdx.x; t0 < 128 * ntn; t0 += gridDim.x) {
;     ...
;               [=](int row, int col, float v) {
;                 float inv = rsqrtf(ss[row] * (1.0f / 1024.0f) + EPSF);
;                 C[(size_t)row * N + col] = f2bf(v * inv);
;               });
	ds_read_b128 v[112:115], v181
	ds_read_b128 v[116:119], v181 offset:1088
	ds_read_b128 v[120:123], v181 offset:2176
	ds_read_b128 v[124:127], v181 offset:3264
	ds_read_b128 v[96:99], v181 offset:4352
	ds_read_b128 v[100:103], v181 offset:5440
	ds_read_b128 v[104:107], v181 offset:6528
	ds_read_b128 v[108:111], v181 offset:7616
	s_add_u32 s66, s64, 0x0
	s_addc_u32 s67, s65, 0
	s_waitcnt lgkmcnt(7)
	global_store_dwordx4 v182, v[112:115], s[66:67]
	s_add_u32 s66, s64, 0x2000
	s_addc_u32 s67, s65, 0
	s_waitcnt lgkmcnt(6)
	global_store_dwordx4 v182, v[116:119], s[66:67]
	s_add_u32 s66, s64, 0x4000
	s_addc_u32 s67, s65, 0
	s_waitcnt lgkmcnt(5)
	global_store_dwordx4 v182, v[120:123], s[66:67]
	s_add_u32 s66, s64, 0x6000
	s_addc_u32 s67, s65, 0
	s_waitcnt lgkmcnt(4)
	global_store_dwordx4 v182, v[124:127], s[66:67]
	s_add_u32 s66, s64, 0x8000
	s_addc_u32 s67, s65, 0
	s_waitcnt lgkmcnt(3)
	global_store_dwordx4 v182, v[96:99], s[66:67]
	s_add_u32 s66, s64, 0xa000
	s_addc_u32 s67, s65, 0
	s_waitcnt lgkmcnt(2)
	global_store_dwordx4 v182, v[100:103], s[66:67]
	s_add_u32 s66, s64, 0xc000
	s_addc_u32 s67, s65, 0
	s_waitcnt lgkmcnt(1)
	global_store_dwordx4 v182, v[104:107], s[66:67]
	s_add_u32 s66, s64, 0xe000
	s_addc_u32 s67, s65, 0
	s_waitcnt lgkmcnt(0)
	global_store_dwordx4 v182, v[108:111], s[66:67]
	v_mul_f32_e32 v48, v184, v48
	v_mul_f32_e32 v49, v184, v49
	v_mul_f32_e32 v50, v184, v50
	v_mul_f32_e32 v51, v184, v51
	v_cvt_pk_bf16_f32 v48, v48, v49
	v_cvt_pk_bf16_f32 v49, v50, v51
	ds_write_b64 v180, v[48:49]
	v_mul_f32_e32 v52, v184, v52
	v_mul_f32_e32 v53, v184, v53
	v_mul_f32_e32 v54, v184, v54
	v_mul_f32_e32 v55, v184, v55
	v_cvt_pk_bf16_f32 v52, v52, v53
	v_cvt_pk_bf16_f32 v53, v54, v55
	ds_write_b64 v180, v[52:53] offset:16
	v_mul_f32_e32 v56, v184, v56
	v_mul_f32_e32 v57, v184, v57
	v_mul_f32_e32 v58, v184, v58
	v_mul_f32_e32 v59, v184, v59
	v_cvt_pk_bf16_f32 v56, v56, v57
	v_cvt_pk_bf16_f32 v57, v58, v59
	ds_write_b64 v180, v[56:57] offset:32
	v_mul_f32_e32 v60, v184, v60
	v_mul_f32_e32 v61, v184, v61
	v_mul_f32_e32 v62, v184, v62
	v_mul_f32_e32 v63, v184, v63
	v_cvt_pk_bf16_f32 v60, v60, v61
	v_cvt_pk_bf16_f32 v61, v62, v63
	ds_write_b64 v180, v[60:61] offset:48
	v_mul_f32_e32 v32, v184, v32
	v_mul_f32_e32 v33, v184, v33
	v_mul_f32_e32 v34, v184, v34
	v_mul_f32_e32 v35, v184, v35
	v_cvt_pk_bf16_f32 v32, v32, v33
	v_cvt_pk_bf16_f32 v33, v34, v35
	ds_write_b64 v180, v[32:33] offset:64
	v_mul_f32_e32 v36, v184, v36
	v_mul_f32_e32 v37, v184, v37
	v_mul_f32_e32 v38, v184, v38
	v_mul_f32_e32 v39, v184, v39
	v_cvt_pk_bf16_f32 v36, v36, v37
	v_cvt_pk_bf16_f32 v37, v38, v39
	ds_write_b64 v180, v[36:37] offset:80
	v_mul_f32_e32 v40, v184, v40
	v_mul_f32_e32 v41, v184, v41
	v_mul_f32_e32 v42, v184, v42
	v_mul_f32_e32 v43, v184, v43
	v_cvt_pk_bf16_f32 v40, v40, v41
	v_cvt_pk_bf16_f32 v41, v42, v43
	ds_write_b64 v180, v[40:41] offset:96
	v_mul_f32_e32 v44, v184, v44
	v_mul_f32_e32 v45, v184, v45
	v_mul_f32_e32 v46, v184, v46
	v_mul_f32_e32 v47, v184, v47
	v_cvt_pk_bf16_f32 v44, v44, v45
	v_cvt_pk_bf16_f32 v45, v46, v47
	ds_write_b64 v180, v[44:45] offset:112
	v_mul_f32_e32 v16, v184, v16
	v_mul_f32_e32 v17, v184, v17
	v_mul_f32_e32 v18, v184, v18
	v_mul_f32_e32 v19, v184, v19
	v_cvt_pk_bf16_f32 v16, v16, v17
	v_cvt_pk_bf16_f32 v17, v18, v19
	ds_write_b64 v180, v[16:17] offset:128
	v_mul_f32_e32 v20, v184, v20
	v_mul_f32_e32 v21, v184, v21
	v_mul_f32_e32 v22, v184, v22
	v_mul_f32_e32 v23, v184, v23
	v_cvt_pk_bf16_f32 v20, v20, v21
	v_cvt_pk_bf16_f32 v21, v22, v23
	ds_write_b64 v180, v[20:21] offset:144
	v_mul_f32_e32 v24, v184, v24
	v_mul_f32_e32 v25, v184, v25
	v_mul_f32_e32 v26, v184, v26
	v_mul_f32_e32 v27, v184, v27
	v_cvt_pk_bf16_f32 v24, v24, v25
	v_cvt_pk_bf16_f32 v25, v26, v27
	ds_write_b64 v180, v[24:25] offset:160
	v_mul_f32_e32 v28, v184, v28
	v_mul_f32_e32 v29, v184, v29
	v_mul_f32_e32 v30, v184, v30
	v_mul_f32_e32 v31, v184, v31
	v_cvt_pk_bf16_f32 v28, v28, v29
	v_cvt_pk_bf16_f32 v29, v30, v31
	ds_write_b64 v180, v[28:29] offset:176
	v_mul_f32_e32 v0, v184, v0
	v_mul_f32_e32 v1, v184, v1
	v_mul_f32_e32 v2, v184, v2
	v_mul_f32_e32 v3, v184, v3
	v_cvt_pk_bf16_f32 v0, v0, v1
	v_cvt_pk_bf16_f32 v1, v2, v3
	ds_write_b64 v180, v[0:1] offset:192
	v_mul_f32_e32 v4, v184, v4
	v_mul_f32_e32 v5, v184, v5
	v_mul_f32_e32 v6, v184, v6
	v_mul_f32_e32 v7, v184, v7
	v_cvt_pk_bf16_f32 v4, v4, v5
	v_cvt_pk_bf16_f32 v5, v6, v7
	ds_write_b64 v180, v[4:5] offset:208
	v_mul_f32_e32 v8, v184, v8
	v_mul_f32_e32 v9, v184, v9
	v_mul_f32_e32 v10, v184, v10
	v_mul_f32_e32 v11, v184, v11
	v_cvt_pk_bf16_f32 v8, v8, v9
	v_cvt_pk_bf16_f32 v9, v10, v11
	ds_write_b64 v180, v[8:9] offset:224
	v_mul_f32_e32 v12, v184, v12
	v_mul_f32_e32 v13, v184, v13
	v_mul_f32_e32 v14, v184, v14
	v_mul_f32_e32 v15, v184, v15
	v_cvt_pk_bf16_f32 v12, v12, v13
	v_cvt_pk_bf16_f32 v13, v14, v15
	ds_write_b64 v180, v[12:13] offset:240
	s_waitcnt lgkmcnt(0)
	ds_read_b128 v[48:51], v181
	ds_read_b128 v[52:55], v181 offset:1088
	ds_read_b128 v[56:59], v181 offset:2176
	ds_read_b128 v[60:63], v181 offset:3264
	ds_read_b128 v[32:35], v181 offset:4352
	ds_read_b128 v[36:39], v181 offset:5440
	ds_read_b128 v[40:43], v181 offset:6528
	ds_read_b128 v[44:47], v181 offset:7616
	s_add_u32 s66, s64, 0x10000
	s_addc_u32 s67, s65, 0
	s_waitcnt lgkmcnt(7)
	global_store_dwordx4 v182, v[48:51], s[66:67]
	s_add_u32 s66, s64, 0x12000
	s_addc_u32 s67, s65, 0
	s_waitcnt lgkmcnt(6)
	global_store_dwordx4 v182, v[52:55], s[66:67]
	s_add_u32 s66, s64, 0x14000
	s_addc_u32 s67, s65, 0
	s_waitcnt lgkmcnt(5)
	global_store_dwordx4 v182, v[56:59], s[66:67]
	s_add_u32 s66, s64, 0x16000
	s_addc_u32 s67, s65, 0
	s_waitcnt lgkmcnt(4)
	global_store_dwordx4 v182, v[60:63], s[66:67]
	s_add_u32 s66, s64, 0x18000
	s_addc_u32 s67, s65, 0
	s_waitcnt lgkmcnt(3)
	global_store_dwordx4 v182, v[32:35], s[66:67]
	s_add_u32 s66, s64, 0x1a000
	s_addc_u32 s67, s65, 0
	s_waitcnt lgkmcnt(2)
	global_store_dwordx4 v182, v[36:39], s[66:67]
	s_add_u32 s66, s64, 0x1c000
	s_addc_u32 s67, s65, 0
	s_waitcnt lgkmcnt(1)
	global_store_dwordx4 v182, v[40:43], s[66:67]
	s_add_u32 s66, s64, 0x1e000
	s_addc_u32 s67, s65, 0
	s_waitcnt lgkmcnt(0)
	global_store_dwordx4 v182, v[44:47], s[66:67]
	v_readlane_b32 s64, v187, 0
	v_readlane_b32 s65, v187, 1
	v_readlane_b32 s66, v187, 2
	v_readlane_b32 s67, v187, 3
	v_readlane_b32 s68, v187, 4
	v_readlane_b32 s69, v187, 5
	v_readlane_b32 s70, v187, 6
	v_readlane_b32 s71, v187, 7
	v_readlane_b32 s72, v187, 8
	v_readlane_b32 s73, v187, 9
	v_readlane_b32 s74, v187, 10
	v_readlane_b32 s75, v187, 11
	v_readlane_b32 s76, v187, 12
	v_readlane_b32 s77, v187, 13
	v_readlane_b32 s78, v187, 14
	v_readlane_b32 s79, v187, 15
	s_nop 7
	s_add_i32 s28, s28, s34
	s_cmpk_lt_i32 s28, 0x200
	s_cbranch_scc0 .LBB0_936
	s_branch .LBB0_923

; #define GA_LOAD(pr_) do { _Pragma("unroll") for (int i = 0; i < 4; ++i) ra[i] = *(const u32x4*)(Ab + (i * 32) * lda + (pr_) * 64); } while (0)
; #define GB_LOAD(kt_) do { const bfr* bk_ = Bb + (kt_) * NB * 32; \
;     _Pragma("unroll") for (int i = 0; i < 4; ++i) rb[i] = *(const u32x4*)(bk_ + (i * 64) * 32); } while (0)
; #define G_STORE(kt_) do { bfr* as_ = S0 + ((kt_) & 1) * GSTAGE; bfr* bs_ = as_ + 128 * 40; \
;     if (apar == ((kt_) & 1)) { _Pragma("unroll") for (int i = 0; i < 4; ++i) *(u32x4*)(as_ + asoff + i * 32 * 40) = ra[i]; } \
;     _Pragma("unroll") for (int i = 0; i < 4; ++i) *(u32x4*)(bs_ + bsoff + i * 64 * 40) = rb[i]; } while (0)
; template <int lda>
; DI void gemm_mainloop(const bfr* __restrict__ A, const bfr* __restrict__ Bt, int NB, int K, int m0, int n0, char* smem, f32x16 (&acc)[2][4]) {
;     ...
;   const int nk = K >> 5;
;   const int arow = tid >> 3, ac8 = tid & 7, apar = ac8 >> 2;
;   const bfr* Ab = A + (m0 + arow) * lda + ac8 * 8;
;   const int asoff = arow * 40 + (ac8 & 3) * 8;
;   const int brow = tid >> 2, bc4 = tid & 3;
;   const bfr* Bb = Bt + (n0 + brow) * 32 + bc4 * 8;
;   const int bsoff = brow * 40 + bc4 * 8;
;     ...
;   GA_LOAD(0);
;   GB_LOAD(0);
;   G_STORE(0);
;   GB_LOAD(1);
;   __syncthreads();
; DI int xcd_tile(int t, int ntn) {
;   const int x = t & 7, li = t >> 3;
;   return (x * 16 + li / ntn) * ntn + (li % ntn);
; }
; DI void phase_gemm_bf16out(const Params& p, const bfr* A, const bfr* Wt, bfr* C, int N, const float* ss, char* smem) {
;     ...
;   for (int t0 = blockIdx.x; t0 < 128 * ntn; t0 += gridDim.x) {
;     const int t = ((gridDim.x & 7) == 0) ? xcd_tile(t0, ntn) : t0;
;     int mt = t / ntn, nt = t % ntn;
;     gemm_tile<1024>(A, Wt, N, 1024, mt * 128, nt * 256, smem,
.LBB0_1176:
	v_readlane_b32 s0, v254, 6
	v_readlane_b32 s1, v254, 7
	s_andn2_b64 vcc, exec, s[0:1]
	s_cbranch_vccnz .LBB0_1192
	s_and_b32 s0, s34, 7
	s_cmp_eq_u32 s0, 0
	s_cselect_b64 s[0:1], -1, 0
	v_cndmask_b32_e64 v0, 0, 1, s[0:1]
	s_add_u32 s6, s10, 0x20080
	s_addc_u32 s7, s11, 0
	v_cmp_ne_u32_e64 s[0:1], 1, v0
	v_mov_b32_e32 v199, 0
	s_mov_b32 s15, 0x10000
	s_mov_b32 s17, 0x20000
	s_mov_b32 s22, 0x30000
	s_movk_i32 s23, 0x1000
	s_mov_b32 s24, 0xfffffc0
	s_movk_i32 s25, 0x80
	s_movk_i32 s26, 0x50
	s_mov_b32 s14, 0x3a800000
	s_mov_b32 s16, 0x358637bd
	s_mov_b32 s27, 0x800000
	s_mov_b32 s28, s46
	s_branch .LBB0_1179
.LBB0_1179:
	s_and_b64 vcc, exec, s[0:1]
	s_mov_b32 s4, s28
	s_cbranch_vccnz .LBB0_1181
	s_ashr_i32 s4, s28, 3
	s_lshr_b32 s18, s4, 29
	s_lshl_b32 s5, s28, 4
	s_add_i32 s18, s4, s18
	s_and_b32 s5, s5, 0x70
	s_lshr_b32 s19, s18, 3
	s_add_i32 s19, s19, s5
	s_and_b32 s18, s18, -8
	s_lshl_b32 s5, s19, 3
	s_sub_i32 s4, s4, s18
	s_add_i32 s4, s5, s4
.LBB0_1181:
	s_ashr_i32 s5, s4, 31
	s_lshr_b32 s5, s5, 29
	s_add_i32 s5, s4, s5
	s_and_b32 s18, s5, 0xfffff8
	s_lshl_b32 s5, s5, 4
	s_and_b32 s30, s5, 0xffffff80
	s_sub_i32 s4, s4, s18
	s_lshl_b32 s29, s4, 8
	s_mov_b32 s31, 0
	s_mov_b64 s[18:19], 0
	s_lshl_b32 s98, s30, 11
	s_add_u32 s98, s10, s98
	s_addc_u32 s99, s11, 0
	s_lshl_b32 s100, s29, 6
	s_add_u32 s100, s12, s100
	s_addc_u32 s101, s13, 0
	v_writelane_b32 v187, s64, 0
	v_writelane_b32 v187, s65, 1
	v_writelane_b32 v187, s66, 2
	v_writelane_b32 v187, s67, 3
	v_writelane_b32 v187, s68, 4
	v_writelane_b32 v187, s69, 5
	v_writelane_b32 v187, s70, 6
	v_writelane_b32 v187, s71, 7
	v_writelane_b32 v187, s72, 8
	v_writelane_b32 v187, s73, 9
	v_writelane_b32 v187, s74, 10
	v_writelane_b32 v187, s75, 11
	v_writelane_b32 v187, s76, 12
	v_writelane_b32 v187, s77, 13
	v_writelane_b32 v187, s78, 14
	v_writelane_b32 v187, s79, 15
	s_mov_b32 s77, s30
	s_mov_b32 s78, s29
	v_lshrrev_b32_e32 v188, 6, v196
	v_and_b32_e32 v189, 63, v196
	v_readfirstlane_b32 s73, v188
	v_lshrrev_b32_e32 v190, 2, v189
	v_bfe_u32 v191, v189, 4, 2
	v_and_b32_e32 v188, 3, v189
	v_xor_b32_e32 v188, v188, v191
	v_lshlrev_b32_e32 v188, 4, v188
	v_lshl_add_u32 v176, v190, 11, v188
	v_add_u32_e32 v177, 0x8000, v176
	v_lshl_add_u32 v178, v190, 6, v188
	v_and_b32_e32 v190, 31, v189
	v_lshrrev_b32_e32 v191, 5, v189
	v_bfe_u32 v188, v189, 2, 2
	v_xor_b32_e32 v188, v188, v191
	v_lshlrev_b32_e32 v188, 4, v188
	v_lshl_add_u32 v179, v190, 6, v188
	s_lshr_b32 s74, s73, 1
	s_lshl_b32 s74, s74, 12
	s_and_b32 s75, s73, 1
	s_lshl_b32 s75, s75, 13
	v_add_u32_e32 v181, s75, v179
	v_add_u32_e32 v179, s74, v179
	v_xor_b32_e32 v182, 32, v181
	v_xor_b32_e32 v180, 32, v179
	s_lshl_b32 s74, s73, 16
	s_add_u32 s64, s98, s74
	s_addc_u32 s65, s99, 0
	s_lshl_b32 s74, s73, 12
	s_add_u32 s66, s100, s74
	s_addc_u32 s67, s101, 0
	s_lshl_b32 s68, s73, 11
	s_lshl_b32 s69, s73, 12
	s_mov_b32 s70, 0
	s_mov_b32 s71, 0
	s_mov_b32 s72, 0
	s_waitcnt lgkmcnt(0)
	s_barrier
	s_mul_i32 s74, s70, 0x6000
	s_add_u32 s75, s74, s68
	s_mov_b32 m0, s75
	s_add_u32 s76, s74, 0x2000
	s_cmp_eq_u32 s70, 2
	s_cselect_b32 s76, 0x10000, s76
	global_load_lds_dwordx4 v176, s[64:65]
	s_add_u32 m0, s75, 0x400
	s_add_u32 s76, s76, s69
	global_load_lds_dwordx4 v177, s[64:65]
	s_mov_b32 m0, s76
	s_add_u32 s64, s64, 64
	s_addc_u32 s65, s65, 0
	global_load_lds_dwordx4 v178, s[66:67]
	global_load_lds_dwordx4 v178, s[66:67] offset:1024
	global_load_lds_dwordx4 v178, s[66:67] offset:2048
	global_load_lds_dwordx4 v178, s[66:67] offset:3072
	s_add_u32 s66, s66, 0x20000
	s_addc_u32 s67, s67, 0
	s_add_u32 s70, s70, 1
	s_cmp_eq_u32 s70, 3
	s_cselect_b32 s70, 0, s70
	s_mul_i32 s74, s70, 0x6000
	s_add_u32 s75, s74, s68
	s_mov_b32 m0, s75
	s_add_u32 s76, s74, 0x2000
	s_cmp_eq_u32 s70, 2
	s_cselect_b32 s76, 0x10000, s76
	global_load_lds_dwordx4 v176, s[64:65]
	s_add_u32 m0, s75, 0x400
	s_add_u32 s76, s76, s69
	global_load_lds_dwordx4 v177, s[64:65]
	s_mov_b32 m0, s76
	s_add_u32 s64, s64, 64
	s_addc_u32 s65, s65, 0
	global_load_lds_dwordx4 v178, s[66:67]
	global_load_lds_dwordx4 v178, s[66:67] offset:1024
	global_load_lds_dwordx4 v178, s[66:67] offset:2048
	global_load_lds_dwordx4 v178, s[66:67] offset:3072
	s_add_u32 s66, s66, 0x20000
	s_addc_u32 s67, s67, 0
	s_add_u32 s70, s70, 1
	s_cmp_eq_u32 s70, 3
	s_cselect_b32 s70, 0, s70
	s_cmp_lt_u32 s46, 0x100
	s_cbranch_scc1 .Lp12_nostag
	s_sleep 8

; #define MFMA32(a, b, c) __builtin_amdgcn_mfma_f32_32x32x16_bf16((a), (b), (c), 0, 0, 0)
; #define GA_LOAD(pr_) do { _Pragma("unroll") for (int i = 0; i < 4; ++i) ra[i] = *(const u32x4*)(Ab + (i * 32) * lda + (pr_) * 64); } while (0)
; #define GB_LOAD(kt_) do { const bfr* bk_ = Bb + (kt_) * NB * 32; \
;     _Pragma("unroll") for (int i = 0; i < 4; ++i) rb[i] = *(const u32x4*)(bk_ + (i * 64) * 32); } while (0)
; #define G_STORE(kt_) do { bfr* as_ = S0 + ((kt_) & 1) * GSTAGE; bfr* bs_ = as_ + 128 * 40; \
;     if (apar == ((kt_) & 1)) { _Pragma("unroll") for (int i = 0; i < 4; ++i) *(u32x4*)(as_ + asoff + i * 32 * 40) = ra[i]; } \
;     _Pragma("unroll") for (int i = 0; i < 4; ++i) *(u32x4*)(bs_ + bsoff + i * 64 * 40) = rb[i]; } while (0)
; template <int lda>
; DI void gemm_mainloop(const bfr* __restrict__ A, const bfr* __restrict__ Bt, int NB, int K, int m0, int n0, char* smem, f32x16 (&acc)[2][4]) {
;     ...
;   for (int kt = 0; kt < nk; ++kt) {
;     if (kt + 1 < nk) G_STORE(kt + 1);
;     if (kt + 2 < nk) {
;       GB_LOAD(kt + 2);
;       if ((kt & 1) == 0) GA_LOAD((kt >> 1) + 1);
;     }
;     const bfr* As = S0 + (kt & 1) * GSTAGE;
;     const bfr* Bs = As + 128 * 40;
; #pragma unroll
;     for (int ks = 0; ks < 2; ++ks) {
;       bf16x8 af[2], bfg[4];
; #pragma unroll
;       for (int i = 0; i < 2; ++i) af[i] = *(const bf16x8*)(As + (wr * 64 + i * 32 + r) * 40 + ks * 16 + hl * 8);
; #pragma unroll
;       for (int j = 0; j < 4; ++j) bfg[j] = *(const bf16x8*)(Bs + (wc * 128 + j * 32 + r) * 40 + ks * 16 + hl * 8);
; #pragma unroll
;       for (int i = 0; i < 2; ++i)
; #pragma unroll
;         for (int j = 0; j < 4; ++j) acc[i][j] = MFMA32(af[i], bfg[j], acc[i][j]);
;     }
;     __syncthreads();
;   }
.Lp12_loop:
	s_waitcnt vmcnt(6)
	s_barrier
	s_mul_i32 s74, s71, 0x6000
	s_add_u32 s75, s74, 0x2000
	s_cmp_eq_u32 s71, 2
	s_cselect_b32 s75, 0x10000, s75
	v_add_u32_e32 v183, s74, v179
	v_add_u32_e32 v185, s75, v181
	v_add_u32_e32 v184, s74, v180
	v_add_u32_e32 v186, s75, v182
	ds_read_b128 v[128:131], v183
	ds_read_b128 v[144:147], v185
	ds_read_b128 v[148:151], v185 offset:2048
	ds_read_b128 v[152:155], v185 offset:4096
	ds_read_b128 v[156:159], v185 offset:6144
	ds_read_b128 v[132:135], v183 offset:2048
	ds_read_b128 v[136:139], v184
	ds_read_b128 v[160:163], v186
	ds_read_b128 v[164:167], v186 offset:2048
	ds_read_b128 v[168:171], v186 offset:4096
	ds_read_b128 v[172:175], v186 offset:6144
	ds_read_b128 v[140:143], v184 offset:2048
	s_add_u32 s71, s71, 1
	s_cmp_eq_u32 s71, 3
	s_cselect_b32 s71, 0, s71
	s_waitcnt lgkmcnt(10)
	v_mfma_f32_32x32x16_bf16 v[112:127], v[144:147], v[128:131], v[112:127]
	s_mul_i32 s74, s70, 0x6000
	s_add_u32 s75, s74, s68
	s_mov_b32 m0, s75
	s_add_u32 s76, s74, 0x2000
	s_cmp_eq_u32 s70, 2
	s_cselect_b32 s76, 0x10000, s76
	global_load_lds_dwordx4 v176, s[64:65]
	s_waitcnt lgkmcnt(9)
	v_mfma_f32_32x32x16_bf16 v[96:111], v[148:151], v[128:131], v[96:111]
	s_add_u32 m0, s75, 0x400
	s_add_u32 s76, s76, s69
	global_load_lds_dwordx4 v177, s[64:65]
	s_waitcnt lgkmcnt(8)
	v_mfma_f32_32x32x16_bf16 v[80:95], v[152:155], v[128:131], v[80:95]
	s_mov_b32 m0, s76
	s_add_u32 s64, s64, 64
	s_addc_u32 s65, s65, 0
	global_load_lds_dwordx4 v178, s[66:67]
	s_waitcnt lgkmcnt(7)
	v_mfma_f32_32x32x16_bf16 v[64:79], v[156:159], v[128:131], v[64:79]
	global_load_lds_dwordx4 v178, s[66:67] offset:1024
	s_waitcnt lgkmcnt(6)
	v_mfma_f32_32x32x16_bf16 v[48:63], v[144:147], v[132:135], v[48:63]
	global_load_lds_dwordx4 v178, s[66:67] offset:2048
	v_mfma_f32_32x32x16_bf16 v[32:47], v[148:151], v[132:135], v[32:47]
	global_load_lds_dwordx4 v178, s[66:67] offset:3072
	s_add_u32 s66, s66, 0x20000
	s_addc_u32 s67, s67, 0
	v_mfma_f32_32x32x16_bf16 v[16:31], v[152:155], v[132:135], v[16:31]
	s_add_u32 s70, s70, 1
	s_cmp_eq_u32 s70, 3
	s_cselect_b32 s70, 0, s70
	v_mfma_f32_32x32x16_bf16 v[0:15], v[156:159], v[132:135], v[0:15]
	s_waitcnt lgkmcnt(4)
	v_mfma_f32_32x32x16_bf16 v[112:127], v[160:163], v[136:139], v[112:127]
	s_waitcnt lgkmcnt(3)
	v_mfma_f32_32x32x16_bf16 v[96:111], v[164:167], v[136:139], v[96:111]
	s_waitcnt lgkmcnt(2)
	v_mfma_f32_32x32x16_bf16 v[80:95], v[168:171], v[136:139], v[80:95]
	s_waitcnt lgkmcnt(1)
	v_mfma_f32_32x32x16_bf16 v[64:79], v[172:175], v[136:139], v[64:79]
	s_waitcnt lgkmcnt(0)
	v_mfma_f32_32x32x16_bf16 v[48:63], v[160:163], v[140:143], v[48:63]
	v_mfma_f32_32x32x16_bf16 v[32:47], v[164:167], v[140:143], v[32:47]
	v_mfma_f32_32x32x16_bf16 v[16:31], v[168:171], v[140:143], v[16:31]
	v_mfma_f32_32x32x16_bf16 v[0:15], v[172:175], v[140:143], v[0:15]
	s_add_u32 s72, s72, 1
	s_cmp_lt_u32 s72, 30
	s_cbranch_scc1 .Lp12_loop
	s_waitcnt vmcnt(6)
	s_barrier
	s_mul_i32 s74, s71, 0x6000
	s_add_u32 s75, s74, 0x2000
	s_cmp_eq_u32 s71, 2
	s_cselect_b32 s75, 0x10000, s75
	v_add_u32_e32 v183, s74, v179
	v_add_u32_e32 v185, s75, v181
	v_add_u32_e32 v184, s74, v180
	v_add_u32_e32 v186, s75, v182
	ds_read_b128 v[128:131], v183
	ds_read_b128 v[144:147], v185
	ds_read_b128 v[148:151], v185 offset:2048
	ds_read_b128 v[152:155], v185 offset:4096
	ds_read_b128 v[156:159], v185 offset:6144
	ds_read_b128 v[132:135], v183 offset:2048
	ds_read_b128 v[136:139], v184
	ds_read_b128 v[160:163], v186
	ds_read_b128 v[164:167], v186 offset:2048
	ds_read_b128 v[168:171], v186 offset:4096
	ds_read_b128 v[172:175], v186 offset:6144
	ds_read_b128 v[140:143], v184 offset:2048
	s_add_u32 s71, s71, 1
	s_cmp_eq_u32 s71, 3
	s_cselect_b32 s71, 0, s71
	s_waitcnt lgkmcnt(10)
	v_mfma_f32_32x32x16_bf16 v[112:127], v[144:147], v[128:131], v[112:127]
	s_waitcnt lgkmcnt(9)
	v_mfma_f32_32x32x16_bf16 v[96:111], v[148:151], v[128:131], v[96:111]
	s_waitcnt lgkmcnt(8)
	v_mfma_f32_32x32x16_bf16 v[80:95], v[152:155], v[128:131], v[80:95]
	s_waitcnt lgkmcnt(7)
	v_mfma_f32_32x32x16_bf16 v[64:79], v[156:159], v[128:131], v[64:79]
	s_waitcnt lgkmcnt(6)
	v_mfma_f32_32x32x16_bf16 v[48:63], v[144:147], v[132:135], v[48:63]
	v_mfma_f32_32x32x16_bf16 v[32:47], v[148:151], v[132:135], v[32:47]
	v_mfma_f32_32x32x16_bf16 v[16:31], v[152:155], v[132:135], v[16:31]
	v_mfma_f32_32x32x16_bf16 v[0:15], v[156:159], v[132:135], v[0:15]
	s_waitcnt lgkmcnt(4)
	v_mfma_f32_32x32x16_bf16 v[112:127], v[160:163], v[136:139], v[112:127]
	s_waitcnt lgkmcnt(3)
	v_mfma_f32_32x32x16_bf16 v[96:111], v[164:167], v[136:139], v[96:111]
	s_waitcnt lgkmcnt(2)
	v_mfma_f32_32x32x16_bf16 v[80:95], v[168:171], v[136:139], v[80:95]
	s_waitcnt lgkmcnt(1)
	v_mfma_f32_32x32x16_bf16 v[64:79], v[172:175], v[136:139], v[64:79]
	s_waitcnt lgkmcnt(0)
	v_mfma_f32_32x32x16_bf16 v[48:63], v[160:163], v[140:143], v[48:63]
	v_mfma_f32_32x32x16_bf16 v[32:47], v[164:167], v[140:143], v[32:47]
	v_mfma_f32_32x32x16_bf16 v[16:31], v[168:171], v[140:143], v[16:31]
	v_mfma_f32_32x32x16_bf16 v[0:15], v[172:175], v[140:143], v[0:15]
	s_waitcnt vmcnt(0)
	s_barrier
; DI bfr f2bf(float a) { return (bfr)(pack2(a, 0.f) & 0xffffu); }
; DI int crow(int reg, int h) { return (reg & 3) + 8 * (reg >> 2) + 4 * h; }
; template <int lda, class Epi>
; DI void gemm_tile(const bfr* __restrict__ A, const bfr* __restrict__ Bt, int NB, int K, int m0, int n0, char* smem, Epi epi) {
;     ...
;   const int lane = tid3 & 63, wid = tid3 >> 6, wr = wid >> 1, wc = wid & 1, r = lane & 31, hl = lane >> 5;
; #pragma unroll
;   for (int i = 0; i < 2; ++i)
; #pragma unroll
;     for (int j = 0; j < 4; ++j)
; #pragma unroll
;       for (int q = 0; q < 16; ++q) {
;         int row = m0 + wr * 64 + i * 32 + crow(q, hl);
;         int col = n0 + wc * 128 + j * 32 + r;
;         epi(row, col, acc[i][j][q]);
;       }
; DI void phase_gemm_bf16out(const Params& p, const bfr* A, const bfr* Wt, bfr* C, int N, const float* ss, char* smem) {
;     ...
;     gemm_tile<1024>(A, Wt, N, 1024, mt * 128, nt * 256, smem,
;               [=](int row, int col, float v) {
;                 float inv = rsqrtf(ss[row] * (1.0f / 1024.0f) + EPSF);
;                 C[(size_t)row * N + col] = f2bf(v * inv);
	s_mul_i32 s74, s71, 0x6000
	s_add_u32 s75, s74, 0x2000
	s_cmp_eq_u32 s71, 2
	s_cselect_b32 s75, 0x10000, s75
	v_add_u32_e32 v183, s74, v179
	v_add_u32_e32 v185, s75, v181
	v_add_u32_e32 v184, s74, v180
	v_add_u32_e32 v186, s75, v182
	ds_read_b128 v[128:131], v183
	ds_read_b128 v[144:147], v185
	ds_read_b128 v[148:151], v185 offset:2048
	ds_read_b128 v[152:155], v185 offset:4096
	ds_read_b128 v[156:159], v185 offset:6144
	ds_read_b128 v[132:135], v183 offset:2048
	ds_read_b128 v[136:139], v184
	ds_read_b128 v[160:163], v186
	ds_read_b128 v[164:167], v186 offset:2048
	ds_read_b128 v[168:171], v186 offset:4096
	ds_read_b128 v[172:175], v186 offset:6144
	ds_read_b128 v[140:143], v184 offset:2048
	s_add_u32 s71, s71, 1
	s_cmp_eq_u32 s71, 3
	s_cselect_b32 s71, 0, s71
	s_waitcnt lgkmcnt(10)
	v_mfma_f32_32x32x16_bf16 v[112:127], v[144:147], v[128:131], v[112:127]
	s_waitcnt lgkmcnt(9)
	v_mfma_f32_32x32x16_bf16 v[96:111], v[148:151], v[128:131], v[96:111]
	s_waitcnt lgkmcnt(8)
	v_mfma_f32_32x32x16_bf16 v[80:95], v[152:155], v[128:131], v[80:95]
	s_waitcnt lgkmcnt(7)
	v_mfma_f32_32x32x16_bf16 v[64:79], v[156:159], v[128:131], v[64:79]
	s_waitcnt lgkmcnt(6)
	v_mfma_f32_32x32x16_bf16 v[48:63], v[144:147], v[132:135], v[48:63]
	v_mfma_f32_32x32x16_bf16 v[32:47], v[148:151], v[132:135], v[32:47]
	v_mfma_f32_32x32x16_bf16 v[16:31], v[152:155], v[132:135], v[16:31]
	v_mfma_f32_32x32x16_bf16 v[0:15], v[156:159], v[132:135], v[0:15]
	s_waitcnt lgkmcnt(4)
	v_mfma_f32_32x32x16_bf16 v[112:127], v[160:163], v[136:139], v[112:127]
	s_waitcnt lgkmcnt(3)
	v_mfma_f32_32x32x16_bf16 v[96:111], v[164:167], v[136:139], v[96:111]
	s_waitcnt lgkmcnt(2)
	v_mfma_f32_32x32x16_bf16 v[80:95], v[168:171], v[136:139], v[80:95]
	s_waitcnt lgkmcnt(1)
	v_mfma_f32_32x32x16_bf16 v[64:79], v[172:175], v[136:139], v[64:79]
	s_waitcnt lgkmcnt(0)
	v_mfma_f32_32x32x16_bf16 v[48:63], v[160:163], v[140:143], v[48:63]
	v_mfma_f32_32x32x16_bf16 v[32:47], v[164:167], v[140:143], v[32:47]
	v_mfma_f32_32x32x16_bf16 v[16:31], v[168:171], v[140:143], v[16:31]
	v_mfma_f32_32x32x16_bf16 v[0:15], v[172:175], v[140:143], v[0:15]
	s_nop 7
	s_nop 3
	s_barrier
	s_load_dwordx2 s[64:65], s[92:93], 0x150
	s_load_dwordx2 s[66:67], s[92:93], 0x140
	v_and_b32_e32 v176, 31, v196
	v_bfe_u32 v177, v196, 5, 1
	s_lshr_b32 s74, s73, 1
	s_lshl_b32 s74, s74, 6
	s_add_u32 s74, s74, s77
	v_add_u32_e32 v178, s74, v176
	s_mul_i32 s76, s73, 8704
	v_mul_u32_u24_e32 v180, 272, v176
	v_lshl_add_u32 v180, v177, 3, v180
	v_add_u32_e32 v180, s76, v180
	v_bfe_u32 v185, v196, 4, 2
	v_and_b32_e32 v186, 15, v196
	v_mul_u32_u24_e32 v181, 272, v185
	v_lshl_add_u32 v181, v186, 4, v181
	v_add_u32_e32 v181, s76, v181
	s_and_b32 s75, s73, 1
	s_lshl_b32 s75, s75, 7
	s_add_u32 s75, s75, s78
	v_add_u32_e32 v179, s74, v185
	v_mul_u32_u24_e32 v179, 0x800, v179
	v_lshl_add_u32 v179, v186, 3, v179
	v_add_lshl_u32 v182, v179, s75, 1
	s_waitcnt lgkmcnt(0)
	s_add_u32 s66, s66, 0x10200
	s_addc_u32 s67, s67, 0
	v_lshlrev_b32_e32 v179, 2, v178
	global_load_dword v183, v179, s[66:67]
	global_load_dword v184, v179, s[66:67] offset:128
	s_waitcnt vmcnt(0)
	v_mul_f32_e32 v183, 0x3a800000, v183
	v_mul_f32_e32 v184, 0x3a800000, v184
	v_add_f32_e32 v183, 0x358637bd, v183
	v_add_f32_e32 v184, 0x358637bd, v184
	v_rsq_f32_e32 v183, v183
	v_rsq_f32_e32 v184, v184
	s_nop 1
	v_mul_f32_e32 v112, v183, v112
	v_mul_f32_e32 v113, v183, v113
	v_mul_f32_e32 v114, v183, v114
	v_mul_f32_e32 v115, v183, v115
	v_cvt_pk_bf16_f32 v112, v112, v113
	v_cvt_pk_bf16_f32 v113, v114, v115
	ds_write_b64 v180, v[112:113]
	v_mul_f32_e32 v116, v183, v116
	v_mul_f32_e32 v117, v183, v117
	v_mul_f32_e32 v118, v183, v118
	v_mul_f32_e32 v119, v183, v119
	v_cvt_pk_bf16_f32 v116, v116, v117
	v_cvt_pk_bf16_f32 v117, v118, v119
	ds_write_b64 v180, v[116:117] offset:16
	v_mul_f32_e32 v120, v183, v120
	v_mul_f32_e32 v121, v183, v121
	v_mul_f32_e32 v122, v183, v122
	v_mul_f32_e32 v123, v183, v123
	v_cvt_pk_bf16_f32 v120, v120, v121
	v_cvt_pk_bf16_f32 v121, v122, v123
	ds_write_b64 v180, v[120:121] offset:32
	v_mul_f32_e32 v124, v183, v124
	v_mul_f32_e32 v125, v183, v125
	v_mul_f32_e32 v126, v183, v126
	v_mul_f32_e32 v127, v183, v127
	v_cvt_pk_bf16_f32 v124, v124, v125
	v_cvt_pk_bf16_f32 v125, v126, v127
	ds_write_b64 v180, v[124:125] offset:48
	v_mul_f32_e32 v96, v183, v96
	v_mul_f32_e32 v97, v183, v97
	v_mul_f32_e32 v98, v183, v98
	v_mul_f32_e32 v99, v183, v99
	v_cvt_pk_bf16_f32 v96, v96, v97
	v_cvt_pk_bf16_f32 v97, v98, v99
	ds_write_b64 v180, v[96:97] offset:64
	v_mul_f32_e32 v100, v183, v100
	v_mul_f32_e32 v101, v183, v101
	v_mul_f32_e32 v102, v183, v102
	v_mul_f32_e32 v103, v183, v103
	v_cvt_pk_bf16_f32 v100, v100, v101
	v_cvt_pk_bf16_f32 v101, v102, v103
	ds_write_b64 v180, v[100:101] offset:80
	v_mul_f32_e32 v104, v183, v104
	v_mul_f32_e32 v105, v183, v105
	v_mul_f32_e32 v106, v183, v106
	v_mul_f32_e32 v107, v183, v107
	v_cvt_pk_bf16_f32 v104, v104, v105
	v_cvt_pk_bf16_f32 v105, v106, v107
	ds_write_b64 v180, v[104:105] offset:96
	v_mul_f32_e32 v108, v183, v108
	v_mul_f32_e32 v109, v183, v109
	v_mul_f32_e32 v110, v183, v110
	v_mul_f32_e32 v111, v183, v111
	v_cvt_pk_bf16_f32 v108, v108, v109
	v_cvt_pk_bf16_f32 v109, v110, v111
	ds_write_b64 v180, v[108:109] offset:112
	v_mul_f32_e32 v80, v183, v80
	v_mul_f32_e32 v81, v183, v81
	v_mul_f32_e32 v82, v183, v82
	v_mul_f32_e32 v83, v183, v83
	v_cvt_pk_bf16_f32 v80, v80, v81
	v_cvt_pk_bf16_f32 v81, v82, v83
	ds_write_b64 v180, v[80:81] offset:128
	v_mul_f32_e32 v84, v183, v84
	v_mul_f32_e32 v85, v183, v85
	v_mul_f32_e32 v86, v183, v86
	v_mul_f32_e32 v87, v183, v87
	v_cvt_pk_bf16_f32 v84, v84, v85
	v_cvt_pk_bf16_f32 v85, v86, v87
	ds_write_b64 v180, v[84:85] offset:144
	v_mul_f32_e32 v88, v183, v88
	v_mul_f32_e32 v89, v183, v89
	v_mul_f32_e32 v90, v183, v90
	v_mul_f32_e32 v91, v183, v91
	v_cvt_pk_bf16_f32 v88, v88, v89
	v_cvt_pk_bf16_f32 v89, v90, v91
	ds_write_b64 v180, v[88:89] offset:160
	v_mul_f32_e32 v92, v183, v92
	v_mul_f32_e32 v93, v183, v93
	v_mul_f32_e32 v94, v183, v94
	v_mul_f32_e32 v95, v183, v95
	v_cvt_pk_bf16_f32 v92, v92, v93
	v_cvt_pk_bf16_f32 v93, v94, v95
	ds_write_b64 v180, v[92:93] offset:176
	v_mul_f32_e32 v64, v183, v64
	v_mul_f32_e32 v65, v183, v65
	v_mul_f32_e32 v66, v183, v66
	v_mul_f32_e32 v67, v183, v67
	v_cvt_pk_bf16_f32 v64, v64, v65
	v_cvt_pk_bf16_f32 v65, v66, v67
	ds_write_b64 v180, v[64:65] offset:192
	v_mul_f32_e32 v68, v183, v68
	v_mul_f32_e32 v69, v183, v69
	v_mul_f32_e32 v70, v183, v70
	v_mul_f32_e32 v71, v183, v71
	v_cvt_pk_bf16_f32 v68, v68, v69
	v_cvt_pk_bf16_f32 v69, v70, v71
	ds_write_b64 v180, v[68:69] offset:208
	v_mul_f32_e32 v72, v183, v72
	v_mul_f32_e32 v73, v183, v73
	v_mul_f32_e32 v74, v183, v74
	v_mul_f32_e32 v75, v183, v75
	v_cvt_pk_bf16_f32 v72, v72, v73
	v_cvt_pk_bf16_f32 v73, v74, v75
	ds_write_b64 v180, v[72:73] offset:224
	v_mul_f32_e32 v76, v183, v76
	v_mul_f32_e32 v77, v183, v77
	v_mul_f32_e32 v78, v183, v78
	v_mul_f32_e32 v79, v183, v79
	v_cvt_pk_bf16_f32 v76, v76, v77
	v_cvt_pk_bf16_f32 v77, v78, v79
	ds_write_b64 v180, v[76:77] offset:240
	s_waitcnt lgkmcnt(0)
; DI bfr f2bf(float a) { return (bfr)(pack2(a, 0.f) & 0xffffu); }
; DI void phase_gemm_bf16out(const Params& p, const bfr* A, const bfr* Wt, bfr* C, int N, const float* ss, char* smem) {
;     ...
;   for (int t0 = blockIdx.x; t0 < 128 * ntn; t0 += gridDim.x) {
;     ...
;               [=](int row, int col, float v) {
;                 float inv = rsqrtf(ss[row] * (1.0f / 1024.0f) + EPSF);
;                 C[(size_t)row * N + col] = f2bf(v * inv);
;               });
	ds_read_b128 v[112:115], v181
	ds_read_b128 v[116:119], v181 offset:1088
	ds_read_b128 v[120:123], v181 offset:2176
	ds_read_b128 v[124:127], v181 offset:3264
	ds_read_b128 v[96:99], v181 offset:4352
	ds_read_b128 v[100:103], v181 offset:5440
	ds_read_b128 v[104:107], v181 offset:6528
	ds_read_b128 v[108:111], v181 offset:7616
	s_add_u32 s66, s64, 0x0
	s_addc_u32 s67, s65, 0
	s_waitcnt lgkmcnt(7)
	global_store_dwordx4 v182, v[112:115], s[66:67]
	s_add_u32 s66, s64, 0x4000
	s_addc_u32 s67, s65, 0
	s_waitcnt lgkmcnt(6)
	global_store_dwordx4 v182, v[116:119], s[66:67]
	s_add_u32 s66, s64, 0x8000
	s_addc_u32 s67, s65, 0
	s_waitcnt lgkmcnt(5)
	global_store_dwordx4 v182, v[120:123], s[66:67]
	s_add_u32 s66, s64, 0xc000
	s_addc_u32 s67, s65, 0
	s_waitcnt lgkmcnt(4)
	global_store_dwordx4 v182, v[124:127], s[66:67]
	s_add_u32 s66, s64, 0x10000
	s_addc_u32 s67, s65, 0
	s_waitcnt lgkmcnt(3)
	global_store_dwordx4 v182, v[96:99], s[66:67]
	s_add_u32 s66, s64, 0x14000
	s_addc_u32 s67, s65, 0
	s_waitcnt lgkmcnt(2)
	global_store_dwordx4 v182, v[100:103], s[66:67]
	s_add_u32 s66, s64, 0x18000
	s_addc_u32 s67, s65, 0
	s_waitcnt lgkmcnt(1)
	global_store_dwordx4 v182, v[104:107], s[66:67]
	s_add_u32 s66, s64, 0x1c000
	s_addc_u32 s67, s65, 0
	s_waitcnt lgkmcnt(0)
	global_store_dwordx4 v182, v[108:111], s[66:67]
	v_mul_f32_e32 v48, v184, v48
	v_mul_f32_e32 v49, v184, v49
	v_mul_f32_e32 v50, v184, v50
	v_mul_f32_e32 v51, v184, v51
	v_cvt_pk_bf16_f32 v48, v48, v49
	v_cvt_pk_bf16_f32 v49, v50, v51
	ds_write_b64 v180, v[48:49]
	v_mul_f32_e32 v52, v184, v52
	v_mul_f32_e32 v53, v184, v53
	v_mul_f32_e32 v54, v184, v54
	v_mul_f32_e32 v55, v184, v55
	v_cvt_pk_bf16_f32 v52, v52, v53
	v_cvt_pk_bf16_f32 v53, v54, v55
	ds_write_b64 v180, v[52:53] offset:16
	v_mul_f32_e32 v56, v184, v56
	v_mul_f32_e32 v57, v184, v57
	v_mul_f32_e32 v58, v184, v58
	v_mul_f32_e32 v59, v184, v59
	v_cvt_pk_bf16_f32 v56, v56, v57
	v_cvt_pk_bf16_f32 v57, v58, v59
	ds_write_b64 v180, v[56:57] offset:32
	v_mul_f32_e32 v60, v184, v60
	v_mul_f32_e32 v61, v184, v61
	v_mul_f32_e32 v62, v184, v62
	v_mul_f32_e32 v63, v184, v63
	v_cvt_pk_bf16_f32 v60, v60, v61
	v_cvt_pk_bf16_f32 v61, v62, v63
	ds_write_b64 v180, v[60:61] offset:48
	v_mul_f32_e32 v32, v184, v32
	v_mul_f32_e32 v33, v184, v33
	v_mul_f32_e32 v34, v184, v34
	v_mul_f32_e32 v35, v184, v35
	v_cvt_pk_bf16_f32 v32, v32, v33
	v_cvt_pk_bf16_f32 v33, v34, v35
	ds_write_b64 v180, v[32:33] offset:64
	v_mul_f32_e32 v36, v184, v36
	v_mul_f32_e32 v37, v184, v37
	v_mul_f32_e32 v38, v184, v38
	v_mul_f32_e32 v39, v184, v39
	v_cvt_pk_bf16_f32 v36, v36, v37
	v_cvt_pk_bf16_f32 v37, v38, v39
	ds_write_b64 v180, v[36:37] offset:80
	v_mul_f32_e32 v40, v184, v40
	v_mul_f32_e32 v41, v184, v41
	v_mul_f32_e32 v42, v184, v42
	v_mul_f32_e32 v43, v184, v43
	v_cvt_pk_bf16_f32 v40, v40, v41
	v_cvt_pk_bf16_f32 v41, v42, v43
	ds_write_b64 v180, v[40:41] offset:96
	v_mul_f32_e32 v44, v184, v44
	v_mul_f32_e32 v45, v184, v45
	v_mul_f32_e32 v46, v184, v46
	v_mul_f32_e32 v47, v184, v47
	v_cvt_pk_bf16_f32 v44, v44, v45
	v_cvt_pk_bf16_f32 v45, v46, v47
	ds_write_b64 v180, v[44:45] offset:112
	v_mul_f32_e32 v16, v184, v16
	v_mul_f32_e32 v17, v184, v17
	v_mul_f32_e32 v18, v184, v18
	v_mul_f32_e32 v19, v184, v19
	v_cvt_pk_bf16_f32 v16, v16, v17
	v_cvt_pk_bf16_f32 v17, v18, v19
	ds_write_b64 v180, v[16:17] offset:128
	v_mul_f32_e32 v20, v184, v20
	v_mul_f32_e32 v21, v184, v21
	v_mul_f32_e32 v22, v184, v22
	v_mul_f32_e32 v23, v184, v23
	v_cvt_pk_bf16_f32 v20, v20, v21
	v_cvt_pk_bf16_f32 v21, v22, v23
	ds_write_b64 v180, v[20:21] offset:144
	v_mul_f32_e32 v24, v184, v24
	v_mul_f32_e32 v25, v184, v25
	v_mul_f32_e32 v26, v184, v26
	v_mul_f32_e32 v27, v184, v27
	v_cvt_pk_bf16_f32 v24, v24, v25
	v_cvt_pk_bf16_f32 v25, v26, v27
	ds_write_b64 v180, v[24:25] offset:160
	v_mul_f32_e32 v28, v184, v28
	v_mul_f32_e32 v29, v184, v29
	v_mul_f32_e32 v30, v184, v30
	v_mul_f32_e32 v31, v184, v31
	v_cvt_pk_bf16_f32 v28, v28, v29
	v_cvt_pk_bf16_f32 v29, v30, v31
	ds_write_b64 v180, v[28:29] offset:176
	v_mul_f32_e32 v0, v184, v0
	v_mul_f32_e32 v1, v184, v1
	v_mul_f32_e32 v2, v184, v2
	v_mul_f32_e32 v3, v184, v3
	v_cvt_pk_bf16_f32 v0, v0, v1
	v_cvt_pk_bf16_f32 v1, v2, v3
	ds_write_b64 v180, v[0:1] offset:192
	v_mul_f32_e32 v4, v184, v4
	v_mul_f32_e32 v5, v184, v5
	v_mul_f32_e32 v6, v184, v6
	v_mul_f32_e32 v7, v184, v7
	v_cvt_pk_bf16_f32 v4, v4, v5
	v_cvt_pk_bf16_f32 v5, v6, v7
	ds_write_b64 v180, v[4:5] offset:208
	v_mul_f32_e32 v8, v184, v8
	v_mul_f32_e32 v9, v184, v9
	v_mul_f32_e32 v10, v184, v10
	v_mul_f32_e32 v11, v184, v11
	v_cvt_pk_bf16_f32 v8, v8, v9
	v_cvt_pk_bf16_f32 v9, v10, v11
	ds_write_b64 v180, v[8:9] offset:224
	v_mul_f32_e32 v12, v184, v12
	v_mul_f32_e32 v13, v184, v13
	v_mul_f32_e32 v14, v184, v14
	v_mul_f32_e32 v15, v184, v15
	v_cvt_pk_bf16_f32 v12, v12, v13
	v_cvt_pk_bf16_f32 v13, v14, v15
	ds_write_b64 v180, v[12:13] offset:240
	s_waitcnt lgkmcnt(0)
	ds_read_b128 v[48:51], v181
	ds_read_b128 v[52:55], v181 offset:1088
	ds_read_b128 v[56:59], v181 offset:2176
	ds_read_b128 v[60:63], v181 offset:3264
	ds_read_b128 v[32:35], v181 offset:4352
	ds_read_b128 v[36:39], v181 offset:5440
	ds_read_b128 v[40:43], v181 offset:6528
	ds_read_b128 v[44:47], v181 offset:7616
	s_add_u32 s66, s64, 0x20000
	s_addc_u32 s67, s65, 0
	s_waitcnt lgkmcnt(7)
	global_store_dwordx4 v182, v[48:51], s[66:67]
	s_add_u32 s66, s64, 0x24000
	s_addc_u32 s67, s65, 0
	s_waitcnt lgkmcnt(6)
	global_store_dwordx4 v182, v[52:55], s[66:67]
	s_add_u32 s66, s64, 0x28000
	s_addc_u32 s67, s65, 0
	s_waitcnt lgkmcnt(5)
	global_store_dwordx4 v182, v[56:59], s[66:67]
	s_add_u32 s66, s64, 0x2c000
	s_addc_u32 s67, s65, 0
	s_waitcnt lgkmcnt(4)
	global_store_dwordx4 v182, v[60:63], s[66:67]
	s_add_u32 s66, s64, 0x30000
	s_addc_u32 s67, s65, 0
	s_waitcnt lgkmcnt(3)
	global_store_dwordx4 v182, v[32:35], s[66:67]
	s_add_u32 s66, s64, 0x34000
	s_addc_u32 s67, s65, 0
	s_waitcnt lgkmcnt(2)
	global_store_dwordx4 v182, v[36:39], s[66:67]
	s_add_u32 s66, s64, 0x38000
	s_addc_u32 s67, s65, 0
	s_waitcnt lgkmcnt(1)
	global_store_dwordx4 v182, v[40:43], s[66:67]
	s_add_u32 s66, s64, 0x3c000
	s_addc_u32 s67, s65, 0
	s_waitcnt lgkmcnt(0)
	global_store_dwordx4 v182, v[44:47], s[66:67]
	v_readlane_b32 s64, v187, 0
	v_readlane_b32 s65, v187, 1
	v_readlane_b32 s66, v187, 2
	v_readlane_b32 s67, v187, 3
	v_readlane_b32 s68, v187, 4
	v_readlane_b32 s69, v187, 5
	v_readlane_b32 s70, v187, 6
	v_readlane_b32 s71, v187, 7
	v_readlane_b32 s72, v187, 8
	v_readlane_b32 s73, v187, 9
	v_readlane_b32 s74, v187, 10
	v_readlane_b32 s75, v187, 11
	v_readlane_b32 s76, v187, 12
	v_readlane_b32 s77, v187, 13
	v_readlane_b32 s78, v187, 14
	v_readlane_b32 s79, v187, 15
	s_nop 7
	s_add_i32 s28, s28, s34
	s_cmpk_lt_i32 s28, 0x400
	s_cbranch_scc0 .LBB0_1192
	s_branch .LBB0_1179

; #define GA_LOAD(pr_) do { _Pragma("unroll") for (int i = 0; i < 4; ++i) ra[i] = *(const u32x4*)(Ab + (i * 32) * lda + (pr_) * 64); } while (0)
; #define GB_LOAD(kt_) do { const bfr* bk_ = Bb + (kt_) * NB * 32; \
;     _Pragma("unroll") for (int i = 0; i < 4; ++i) rb[i] = *(const u32x4*)(bk_ + (i * 64) * 32); } while (0)
; #define G_STORE(kt_) do { bfr* as_ = S0 + ((kt_) & 1) * GSTAGE; bfr* bs_ = as_ + 128 * 40; \
;     if (apar == ((kt_) & 1)) { _Pragma("unroll") for (int i = 0; i < 4; ++i) *(u32x4*)(as_ + asoff + i * 32 * 40) = ra[i]; } \
;     _Pragma("unroll") for (int i = 0; i < 4; ++i) *(u32x4*)(bs_ + bsoff + i * 64 * 40) = rb[i]; } while (0)
; template <int lda>
; DI void gemm_mainloop(const bfr* __restrict__ A, const bfr* __restrict__ Bt, int NB, int K, int m0, int n0, char* smem, f32x16 (&acc)[2][4]) {
;     ...
;   const int nk = K >> 5;
;   const int arow = tid >> 3, ac8 = tid & 7, apar = ac8 >> 2;
;   const bfr* Ab = A + (m0 + arow) * lda + ac8 * 8;
;   const int asoff = arow * 40 + (ac8 & 3) * 8;
;   const int brow = tid >> 2, bc4 = tid & 3;
;   const bfr* Bb = Bt + (n0 + brow) * 32 + bc4 * 8;
;   const int bsoff = brow * 40 + bc4 * 8;
;     ...
;   GA_LOAD(0);
;   GB_LOAD(0);
;   G_STORE(0);
;   GB_LOAD(1);
;   __syncthreads();
; DI int xcd_tile(int t, int ntn) {
;   const int x = t & 7, li = t >> 3;
;   return (x * 16 + li / ntn) * ntn + (li % ntn);
; }
; DI void phase_gemm_bf16out(const Params& p, const bfr* A, const bfr* Wt, bfr* C, int N, const float* ss, char* smem) {
;     ...
;   for (int t0 = blockIdx.x; t0 < 128 * ntn; t0 += gridDim.x) {
;     const int t = ((gridDim.x & 7) == 0) ? xcd_tile(t0, ntn) : t0;
;     int mt = t / ntn, nt = t % ntn;
;     gemm_tile<1024>(A, Wt, N, 1024, mt * 128, nt * 256, smem,
.LBB0_1543:
	s_cmpk_gt_i32 s46, 0x1ff
	s_cbranch_scc1 .LBB0_1559
	s_and_b32 s0, s34, 7
	s_cmp_eq_u32 s0, 0
	s_cselect_b64 s[0:1], -1, 0
	v_cndmask_b32_e64 v0, 0, 1, s[0:1]
	s_add_u32 s6, s10, 0x20080
	s_addc_u32 s7, s11, 0
	v_cmp_ne_u32_e64 s[0:1], 1, v0
	v_mov_b32_e32 v201, 0
	s_mov_b32 s17, 0x10000
	s_mov_b32 s19, 0x20000
	s_mov_b32 s24, 0x30000
	s_movk_i32 s25, 0x1000
	s_mov_b32 s26, 0xfffffc0
	s_movk_i32 s27, 0x80
	s_movk_i32 s28, 0x50
	s_mov_b32 s16, 0x3a800000
	s_mov_b32 s18, 0x358637bd
	s_mov_b32 s29, 0x800000
	s_mov_b32 s30, s46
	s_branch .LBB0_1546
.LBB0_1546:
	s_and_b64 vcc, exec, s[0:1]
	s_mov_b32 s4, s30
	s_cbranch_vccnz .LBB0_1548
	s_ashr_i32 s4, s30, 3
	s_lshr_b32 s20, s4, 30
	s_lshl_b32 s5, s30, 4
	s_add_i32 s20, s4, s20
	s_and_b32 s5, s5, 0x70
	s_lshr_b32 s21, s20, 2
	s_add_i32 s21, s21, s5
	s_and_b32 s20, s20, -4
	s_lshl_b32 s5, s21, 2
	s_sub_i32 s4, s4, s20
	s_add_i32 s4, s5, s4
.LBB0_1548:
	s_ashr_i32 s5, s4, 31
	s_lshr_b32 s5, s5, 30
	s_add_i32 s5, s4, s5
	s_and_b32 s20, s5, 0xfffffc
	s_lshl_b32 s5, s5, 5
	s_and_b32 s33, s5, 0xffffff80
	s_sub_i32 s4, s4, s20
	s_lshl_b32 s31, s4, 8
	s_mov_b32 s36, 0
	s_mov_b64 s[20:21], 0
	s_lshl_b32 s98, s33, 11
	s_add_u32 s98, s10, s98
	s_addc_u32 s99, s11, 0
	s_lshl_b32 s100, s31, 6
	s_add_u32 s100, s14, s100
	s_addc_u32 s101, s15, 0
	v_writelane_b32 v187, s64, 0
	v_writelane_b32 v187, s65, 1
	v_writelane_b32 v187, s66, 2
	v_writelane_b32 v187, s67, 3
	v_writelane_b32 v187, s68, 4
	v_writelane_b32 v187, s69, 5
	v_writelane_b32 v187, s70, 6
	v_writelane_b32 v187, s71, 7
	v_writelane_b32 v187, s72, 8
	v_writelane_b32 v187, s73, 9
	v_writelane_b32 v187, s74, 10
	v_writelane_b32 v187, s75, 11
	v_writelane_b32 v187, s76, 12
	v_writelane_b32 v187, s77, 13
	v_writelane_b32 v187, s78, 14
	v_writelane_b32 v187, s79, 15
	s_mov_b32 s77, s33
	s_mov_b32 s78, s31
	v_lshrrev_b32_e32 v188, 6, v196
	v_and_b32_e32 v189, 63, v196
	v_readfirstlane_b32 s73, v188
	v_lshrrev_b32_e32 v190, 2, v189
	v_bfe_u32 v191, v189, 4, 2
	v_and_b32_e32 v188, 3, v189
	v_xor_b32_e32 v188, v188, v191
	v_lshlrev_b32_e32 v188, 4, v188
	v_lshl_add_u32 v176, v190, 11, v188
	v_add_u32_e32 v177, 0x8000, v176
	v_lshl_add_u32 v178, v190, 6, v188
	v_and_b32_e32 v190, 31, v189
	v_lshrrev_b32_e32 v191, 5, v189
	v_bfe_u32 v188, v189, 2, 2
	v_xor_b32_e32 v188, v188, v191
	v_lshlrev_b32_e32 v188, 4, v188
	v_lshl_add_u32 v179, v190, 6, v188
	s_lshr_b32 s74, s73, 1
	s_lshl_b32 s74, s74, 12
	s_and_b32 s75, s73, 1
	s_lshl_b32 s75, s75, 13
	v_add_u32_e32 v181, s75, v179
	v_add_u32_e32 v179, s74, v179
	v_xor_b32_e32 v182, 32, v181
	v_xor_b32_e32 v180, 32, v179
	s_lshl_b32 s74, s73, 16
	s_add_u32 s64, s98, s74
	s_addc_u32 s65, s99, 0
	s_lshl_b32 s74, s73, 12
	s_add_u32 s66, s100, s74
	s_addc_u32 s67, s101, 0
	s_lshl_b32 s68, s73, 11
	s_lshl_b32 s69, s73, 12
	s_mov_b32 s70, 0
	s_mov_b32 s71, 0
	s_mov_b32 s72, 0
	s_waitcnt lgkmcnt(0)
	s_barrier
	s_mul_i32 s74, s70, 0x6000
	s_add_u32 s75, s74, s68
	s_mov_b32 m0, s75
	s_add_u32 s76, s74, 0x2000
	s_cmp_eq_u32 s70, 2
	s_cselect_b32 s76, 0x10000, s76
	global_load_lds_dwordx4 v176, s[64:65]
	s_add_u32 m0, s75, 0x400
	s_add_u32 s76, s76, s69
	global_load_lds_dwordx4 v177, s[64:65]
	s_mov_b32 m0, s76
	s_add_u32 s64, s64, 64
	s_addc_u32 s65, s65, 0
	global_load_lds_dwordx4 v178, s[66:67]
	global_load_lds_dwordx4 v178, s[66:67] offset:1024
	global_load_lds_dwordx4 v178, s[66:67] offset:2048
	global_load_lds_dwordx4 v178, s[66:67] offset:3072
	s_add_u32 s66, s66, 0x10000
	s_addc_u32 s67, s67, 0
	s_add_u32 s70, s70, 1
	s_cmp_eq_u32 s70, 3
	s_cselect_b32 s70, 0, s70
	s_mul_i32 s74, s70, 0x6000
	s_add_u32 s75, s74, s68
	s_mov_b32 m0, s75
	s_add_u32 s76, s74, 0x2000
	s_cmp_eq_u32 s70, 2
	s_cselect_b32 s76, 0x10000, s76
	global_load_lds_dwordx4 v176, s[64:65]
	s_add_u32 m0, s75, 0x400
	s_add_u32 s76, s76, s69
	global_load_lds_dwordx4 v177, s[64:65]
	s_mov_b32 m0, s76
	s_add_u32 s64, s64, 64
	s_addc_u32 s65, s65, 0
	global_load_lds_dwordx4 v178, s[66:67]
	global_load_lds_dwordx4 v178, s[66:67] offset:1024
	global_load_lds_dwordx4 v178, s[66:67] offset:2048
	global_load_lds_dwordx4 v178, s[66:67] offset:3072
	s_add_u32 s66, s66, 0x10000
	s_addc_u32 s67, s67, 0
	s_add_u32 s70, s70, 1
	s_cmp_eq_u32 s70, 3
	s_cselect_b32 s70, 0, s70
	s_cmp_lt_u32 s46, 0x100
	s_cbranch_scc1 .Lp17_nostag
	s_sleep 8

; #define MFMA32(a, b, c) __builtin_amdgcn_mfma_f32_32x32x16_bf16((a), (b), (c), 0, 0, 0)
; #define GA_LOAD(pr_) do { _Pragma("unroll") for (int i = 0; i < 4; ++i) ra[i] = *(const u32x4*)(Ab + (i * 32) * lda + (pr_) * 64); } while (0)
; #define GB_LOAD(kt_) do { const bfr* bk_ = Bb + (kt_) * NB * 32; \
;     _Pragma("unroll") for (int i = 0; i < 4; ++i) rb[i] = *(const u32x4*)(bk_ + (i * 64) * 32); } while (0)
; #define G_STORE(kt_) do { bfr* as_ = S0 + ((kt_) & 1) * GSTAGE; bfr* bs_ = as_ + 128 * 40; \
;     if (apar == ((kt_) & 1)) { _Pragma("unroll") for (int i = 0; i < 4; ++i) *(u32x4*)(as_ + asoff + i * 32 * 40) = ra[i]; } \
;     _Pragma("unroll") for (int i = 0; i < 4; ++i) *(u32x4*)(bs_ + bsoff + i * 64 * 40) = rb[i]; } while (0)
; template <int lda>
; DI void gemm_mainloop(const bfr* __restrict__ A, const bfr* __restrict__ Bt, int NB, int K, int m0, int n0, char* smem, f32x16 (&acc)[2][4]) {
;     ...
;   for (int kt = 0; kt < nk; ++kt) {
;     if (kt + 1 < nk) G_STORE(kt + 1);
;     if (kt + 2 < nk) {
;       GB_LOAD(kt + 2);
;       if ((kt & 1) == 0) GA_LOAD((kt >> 1) + 1);
;     }
;     const bfr* As = S0 + (kt & 1) * GSTAGE;
;     const bfr* Bs = As + 128 * 40;
; #pragma unroll
;     for (int ks = 0; ks < 2; ++ks) {
;       bf16x8 af[2], bfg[4];
; #pragma unroll
;       for (int i = 0; i < 2; ++i) af[i] = *(const bf16x8*)(As + (wr * 64 + i * 32 + r) * 40 + ks * 16 + hl * 8);
; #pragma unroll
;       for (int j = 0; j < 4; ++j) bfg[j] = *(const bf16x8*)(Bs + (wc * 128 + j * 32 + r) * 40 + ks * 16 + hl * 8);
; #pragma unroll
;       for (int i = 0; i < 2; ++i)
; #pragma unroll
;         for (int j = 0; j < 4; ++j) acc[i][j] = MFMA32(af[i], bfg[j], acc[i][j]);
;     }
;     __syncthreads();
;   }
.Lp17_loop:
	s_waitcnt vmcnt(6)
	s_barrier
	s_mul_i32 s74, s71, 0x6000
	s_add_u32 s75, s74, 0x2000
	s_cmp_eq_u32 s71, 2
	s_cselect_b32 s75, 0x10000, s75
	v_add_u32_e32 v183, s74, v179
	v_add_u32_e32 v185, s75, v181
	v_add_u32_e32 v184, s74, v180
	v_add_u32_e32 v186, s75, v182
	ds_read_b128 v[128:131], v183
	ds_read_b128 v[144:147], v185
	ds_read_b128 v[148:151], v185 offset:2048
	ds_read_b128 v[152:155], v185 offset:4096
	ds_read_b128 v[156:159], v185 offset:6144
	ds_read_b128 v[132:135], v183 offset:2048
	ds_read_b128 v[136:139], v184
	ds_read_b128 v[160:163], v186
	ds_read_b128 v[164:167], v186 offset:2048
	ds_read_b128 v[168:171], v186 offset:4096
	ds_read_b128 v[172:175], v186 offset:6144
	ds_read_b128 v[140:143], v184 offset:2048
	s_add_u32 s71, s71, 1
	s_cmp_eq_u32 s71, 3
	s_cselect_b32 s71, 0, s71
	s_waitcnt lgkmcnt(10)
	v_mfma_f32_32x32x16_bf16 v[112:127], v[144:147], v[128:131], v[112:127]
	s_mul_i32 s74, s70, 0x6000
	s_add_u32 s75, s74, s68
	s_mov_b32 m0, s75
	s_add_u32 s76, s74, 0x2000
	s_cmp_eq_u32 s70, 2
	s_cselect_b32 s76, 0x10000, s76
	global_load_lds_dwordx4 v176, s[64:65]
	s_waitcnt lgkmcnt(9)
	v_mfma_f32_32x32x16_bf16 v[96:111], v[148:151], v[128:131], v[96:111]
	s_add_u32 m0, s75, 0x400
	s_add_u32 s76, s76, s69
	global_load_lds_dwordx4 v177, s[64:65]
	s_waitcnt lgkmcnt(8)
	v_mfma_f32_32x32x16_bf16 v[80:95], v[152:155], v[128:131], v[80:95]
	s_mov_b32 m0, s76
	s_add_u32 s64, s64, 64
	s_addc_u32 s65, s65, 0
	global_load_lds_dwordx4 v178, s[66:67]
	s_waitcnt lgkmcnt(7)
	v_mfma_f32_32x32x16_bf16 v[64:79], v[156:159], v[128:131], v[64:79]
	global_load_lds_dwordx4 v178, s[66:67] offset:1024
	s_waitcnt lgkmcnt(6)
	v_mfma_f32_32x32x16_bf16 v[48:63], v[144:147], v[132:135], v[48:63]
	global_load_lds_dwordx4 v178, s[66:67] offset:2048
	v_mfma_f32_32x32x16_bf16 v[32:47], v[148:151], v[132:135], v[32:47]
	global_load_lds_dwordx4 v178, s[66:67] offset:3072
	s_add_u32 s66, s66, 0x10000
	s_addc_u32 s67, s67, 0
	v_mfma_f32_32x32x16_bf16 v[16:31], v[152:155], v[132:135], v[16:31]
	s_add_u32 s70, s70, 1
	s_cmp_eq_u32 s70, 3
	s_cselect_b32 s70, 0, s70
	v_mfma_f32_32x32x16_bf16 v[0:15], v[156:159], v[132:135], v[0:15]
	s_waitcnt lgkmcnt(4)
	v_mfma_f32_32x32x16_bf16 v[112:127], v[160:163], v[136:139], v[112:127]
	s_waitcnt lgkmcnt(3)
	v_mfma_f32_32x32x16_bf16 v[96:111], v[164:167], v[136:139], v[96:111]
	s_waitcnt lgkmcnt(2)
	v_mfma_f32_32x32x16_bf16 v[80:95], v[168:171], v[136:139], v[80:95]
	s_waitcnt lgkmcnt(1)
	v_mfma_f32_32x32x16_bf16 v[64:79], v[172:175], v[136:139], v[64:79]
	s_waitcnt lgkmcnt(0)
	v_mfma_f32_32x32x16_bf16 v[48:63], v[160:163], v[140:143], v[48:63]
	v_mfma_f32_32x32x16_bf16 v[32:47], v[164:167], v[140:143], v[32:47]
	v_mfma_f32_32x32x16_bf16 v[16:31], v[168:171], v[140:143], v[16:31]
	v_mfma_f32_32x32x16_bf16 v[0:15], v[172:175], v[140:143], v[0:15]
	s_add_u32 s72, s72, 1
	s_cmp_lt_u32 s72, 30
	s_cbranch_scc1 .Lp17_loop
	s_waitcnt vmcnt(6)
	s_barrier
	s_mul_i32 s74, s71, 0x6000
	s_add_u32 s75, s74, 0x2000
	s_cmp_eq_u32 s71, 2
	s_cselect_b32 s75, 0x10000, s75
	v_add_u32_e32 v183, s74, v179
	v_add_u32_e32 v185, s75, v181
	v_add_u32_e32 v184, s74, v180
	v_add_u32_e32 v186, s75, v182
	ds_read_b128 v[128:131], v183
	ds_read_b128 v[144:147], v185
	ds_read_b128 v[148:151], v185 offset:2048
	ds_read_b128 v[152:155], v185 offset:4096
	ds_read_b128 v[156:159], v185 offset:6144
	ds_read_b128 v[132:135], v183 offset:2048
	ds_read_b128 v[136:139], v184
	ds_read_b128 v[160:163], v186
	ds_read_b128 v[164:167], v186 offset:2048
	ds_read_b128 v[168:171], v186 offset:4096
	ds_read_b128 v[172:175], v186 offset:6144
	ds_read_b128 v[140:143], v184 offset:2048
	s_add_u32 s71, s71, 1
	s_cmp_eq_u32 s71, 3
	s_cselect_b32 s71, 0, s71
	s_waitcnt lgkmcnt(10)
	v_mfma_f32_32x32x16_bf16 v[112:127], v[144:147], v[128:131], v[112:127]
	s_waitcnt lgkmcnt(9)
	v_mfma_f32_32x32x16_bf16 v[96:111], v[148:151], v[128:131], v[96:111]
	s_waitcnt lgkmcnt(8)
	v_mfma_f32_32x32x16_bf16 v[80:95], v[152:155], v[128:131], v[80:95]
	s_waitcnt lgkmcnt(7)
	v_mfma_f32_32x32x16_bf16 v[64:79], v[156:159], v[128:131], v[64:79]
	s_waitcnt lgkmcnt(6)
	v_mfma_f32_32x32x16_bf16 v[48:63], v[144:147], v[132:135], v[48:63]
	v_mfma_f32_32x32x16_bf16 v[32:47], v[148:151], v[132:135], v[32:47]
	v_mfma_f32_32x32x16_bf16 v[16:31], v[152:155], v[132:135], v[16:31]
	v_mfma_f32_32x32x16_bf16 v[0:15], v[156:159], v[132:135], v[0:15]
	s_waitcnt lgkmcnt(4)
	v_mfma_f32_32x32x16_bf16 v[112:127], v[160:163], v[136:139], v[112:127]
	s_waitcnt lgkmcnt(3)
	v_mfma_f32_32x32x16_bf16 v[96:111], v[164:167], v[136:139], v[96:111]
	s_waitcnt lgkmcnt(2)
	v_mfma_f32_32x32x16_bf16 v[80:95], v[168:171], v[136:139], v[80:95]
	s_waitcnt lgkmcnt(1)
	v_mfma_f32_32x32x16_bf16 v[64:79], v[172:175], v[136:139], v[64:79]
	s_waitcnt lgkmcnt(0)
	v_mfma_f32_32x32x16_bf16 v[48:63], v[160:163], v[140:143], v[48:63]
	v_mfma_f32_32x32x16_bf16 v[32:47], v[164:167], v[140:143], v[32:47]
	v_mfma_f32_32x32x16_bf16 v[16:31], v[168:171], v[140:143], v[16:31]
	v_mfma_f32_32x32x16_bf16 v[0:15], v[172:175], v[140:143], v[0:15]
	s_waitcnt vmcnt(0)
	s_barrier
; DI bfr f2bf(float a) { return (bfr)(pack2(a, 0.f) & 0xffffu); }
; DI int crow(int reg, int h) { return (reg & 3) + 8 * (reg >> 2) + 4 * h; }
; template <int lda, class Epi>
; DI void gemm_tile(const bfr* __restrict__ A, const bfr* __restrict__ Bt, int NB, int K, int m0, int n0, char* smem, Epi epi) {
;     ...
;   const int lane = tid3 & 63, wid = tid3 >> 6, wr = wid >> 1, wc = wid & 1, r = lane & 31, hl = lane >> 5;
; #pragma unroll
;   for (int i = 0; i < 2; ++i)
; #pragma unroll
;     for (int j = 0; j < 4; ++j)
; #pragma unroll
;       for (int q = 0; q < 16; ++q) {
;         int row = m0 + wr * 64 + i * 32 + crow(q, hl);
;         int col = n0 + wc * 128 + j * 32 + r;
;         epi(row, col, acc[i][j][q]);
;       }
; DI void phase_gemm_bf16out(const Params& p, const bfr* A, const bfr* Wt, bfr* C, int N, const float* ss, char* smem) {
;     ...
;     gemm_tile<1024>(A, Wt, N, 1024, mt * 128, nt * 256, smem,
;               [=](int row, int col, float v) {
;                 float inv = rsqrtf(ss[row] * (1.0f / 1024.0f) + EPSF);
;                 C[(size_t)row * N + col] = f2bf(v * inv);
	s_mul_i32 s74, s71, 0x6000
	s_add_u32 s75, s74, 0x2000
	s_cmp_eq_u32 s71, 2
	s_cselect_b32 s75, 0x10000, s75
	v_add_u32_e32 v183, s74, v179
	v_add_u32_e32 v185, s75, v181
	v_add_u32_e32 v184, s74, v180
	v_add_u32_e32 v186, s75, v182
	ds_read_b128 v[128:131], v183
	ds_read_b128 v[144:147], v185
	ds_read_b128 v[148:151], v185 offset:2048
	ds_read_b128 v[152:155], v185 offset:4096
	ds_read_b128 v[156:159], v185 offset:6144
	ds_read_b128 v[132:135], v183 offset:2048
	ds_read_b128 v[136:139], v184
	ds_read_b128 v[160:163], v186
	ds_read_b128 v[164:167], v186 offset:2048
	ds_read_b128 v[168:171], v186 offset:4096
	ds_read_b128 v[172:175], v186 offset:6144
	ds_read_b128 v[140:143], v184 offset:2048
	s_add_u32 s71, s71, 1
	s_cmp_eq_u32 s71, 3
	s_cselect_b32 s71, 0, s71
	s_waitcnt lgkmcnt(10)
	v_mfma_f32_32x32x16_bf16 v[112:127], v[144:147], v[128:131], v[112:127]
	s_waitcnt lgkmcnt(9)
	v_mfma_f32_32x32x16_bf16 v[96:111], v[148:151], v[128:131], v[96:111]
	s_waitcnt lgkmcnt(8)
	v_mfma_f32_32x32x16_bf16 v[80:95], v[152:155], v[128:131], v[80:95]
	s_waitcnt lgkmcnt(7)
	v_mfma_f32_32x32x16_bf16 v[64:79], v[156:159], v[128:131], v[64:79]
	s_waitcnt lgkmcnt(6)
	v_mfma_f32_32x32x16_bf16 v[48:63], v[144:147], v[132:135], v[48:63]
	v_mfma_f32_32x32x16_bf16 v[32:47], v[148:151], v[132:135], v[32:47]
	v_mfma_f32_32x32x16_bf16 v[16:31], v[152:155], v[132:135], v[16:31]
	v_mfma_f32_32x32x16_bf16 v[0:15], v[156:159], v[132:135], v[0:15]
	s_waitcnt lgkmcnt(4)
	v_mfma_f32_32x32x16_bf16 v[112:127], v[160:163], v[136:139], v[112:127]
	s_waitcnt lgkmcnt(3)
	v_mfma_f32_32x32x16_bf16 v[96:111], v[164:167], v[136:139], v[96:111]
	s_waitcnt lgkmcnt(2)
	v_mfma_f32_32x32x16_bf16 v[80:95], v[168:171], v[136:139], v[80:95]
	s_waitcnt lgkmcnt(1)
	v_mfma_f32_32x32x16_bf16 v[64:79], v[172:175], v[136:139], v[64:79]
	s_waitcnt lgkmcnt(0)
	v_mfma_f32_32x32x16_bf16 v[48:63], v[160:163], v[140:143], v[48:63]
	v_mfma_f32_32x32x16_bf16 v[32:47], v[164:167], v[140:143], v[32:47]
	v_mfma_f32_32x32x16_bf16 v[16:31], v[168:171], v[140:143], v[16:31]
	v_mfma_f32_32x32x16_bf16 v[0:15], v[172:175], v[140:143], v[0:15]
	s_nop 7
	s_nop 3
	s_barrier
	s_load_dwordx2 s[64:65], s[92:93], 0x160
	s_load_dwordx2 s[66:67], s[92:93], 0x140
	v_and_b32_e32 v176, 31, v196
	v_bfe_u32 v177, v196, 5, 1
	s_lshr_b32 s74, s73, 1
	s_lshl_b32 s74, s74, 6
	s_add_u32 s74, s74, s77
	v_add_u32_e32 v178, s74, v176
	s_mul_i32 s76, s73, 8704
	v_mul_u32_u24_e32 v180, 272, v176
	v_lshl_add_u32 v180, v177, 3, v180
	v_add_u32_e32 v180, s76, v180
	v_bfe_u32 v185, v196, 4, 2
	v_and_b32_e32 v186, 15, v196
	v_mul_u32_u24_e32 v181, 272, v185
	v_lshl_add_u32 v181, v186, 4, v181
	v_add_u32_e32 v181, s76, v181
	s_and_b32 s75, s73, 1
	s_lshl_b32 s75, s75, 7
	s_add_u32 s75, s75, s78
	v_add_u32_e32 v179, s74, v185
	v_mul_u32_u24_e32 v179, 0x400, v179
	v_lshl_add_u32 v179, v186, 3, v179
	v_add_lshl_u32 v182, v179, s75, 1
	s_waitcnt lgkmcnt(0)
	s_add_u32 s66, s66, 0x20400
	s_addc_u32 s67, s67, 0
	v_lshlrev_b32_e32 v179, 2, v178
	global_load_dword v183, v179, s[66:67]
	global_load_dword v184, v179, s[66:67] offset:128
	s_waitcnt vmcnt(0)
	v_mul_f32_e32 v183, 0x3a800000, v183
	v_mul_f32_e32 v184, 0x3a800000, v184
	v_add_f32_e32 v183, 0x358637bd, v183
	v_add_f32_e32 v184, 0x358637bd, v184
	v_rsq_f32_e32 v183, v183
	v_rsq_f32_e32 v184, v184
	s_nop 1
	v_mul_f32_e32 v112, v183, v112
	v_mul_f32_e32 v113, v183, v113
	v_mul_f32_e32 v114, v183, v114
	v_mul_f32_e32 v115, v183, v115
	v_cvt_pk_bf16_f32 v112, v112, v113
	v_cvt_pk_bf16_f32 v113, v114, v115
	ds_write_b64 v180, v[112:113]
	v_mul_f32_e32 v116, v183, v116
	v_mul_f32_e32 v117, v183, v117
	v_mul_f32_e32 v118, v183, v118
	v_mul_f32_e32 v119, v183, v119
	v_cvt_pk_bf16_f32 v116, v116, v117
	v_cvt_pk_bf16_f32 v117, v118, v119
	ds_write_b64 v180, v[116:117] offset:16
	v_mul_f32_e32 v120, v183, v120
	v_mul_f32_e32 v121, v183, v121
	v_mul_f32_e32 v122, v183, v122
	v_mul_f32_e32 v123, v183, v123
	v_cvt_pk_bf16_f32 v120, v120, v121
	v_cvt_pk_bf16_f32 v121, v122, v123
	ds_write_b64 v180, v[120:121] offset:32
	v_mul_f32_e32 v124, v183, v124
	v_mul_f32_e32 v125, v183, v125
	v_mul_f32_e32 v126, v183, v126
	v_mul_f32_e32 v127, v183, v127
	v_cvt_pk_bf16_f32 v124, v124, v125
	v_cvt_pk_bf16_f32 v125, v126, v127
	ds_write_b64 v180, v[124:125] offset:48
	v_mul_f32_e32 v96, v183, v96
	v_mul_f32_e32 v97, v183, v97
	v_mul_f32_e32 v98, v183, v98
	v_mul_f32_e32 v99, v183, v99
	v_cvt_pk_bf16_f32 v96, v96, v97
	v_cvt_pk_bf16_f32 v97, v98, v99
	ds_write_b64 v180, v[96:97] offset:64
	v_mul_f32_e32 v100, v183, v100
	v_mul_f32_e32 v101, v183, v101
	v_mul_f32_e32 v102, v183, v102
	v_mul_f32_e32 v103, v183, v103
	v_cvt_pk_bf16_f32 v100, v100, v101
	v_cvt_pk_bf16_f32 v101, v102, v103
	ds_write_b64 v180, v[100:101] offset:80
	v_mul_f32_e32 v104, v183, v104
	v_mul_f32_e32 v105, v183, v105
	v_mul_f32_e32 v106, v183, v106
	v_mul_f32_e32 v107, v183, v107
	v_cvt_pk_bf16_f32 v104, v104, v105
	v_cvt_pk_bf16_f32 v105, v106, v107
	ds_write_b64 v180, v[104:105] offset:96
	v_mul_f32_e32 v108, v183, v108
	v_mul_f32_e32 v109, v183, v109
	v_mul_f32_e32 v110, v183, v110
	v_mul_f32_e32 v111, v183, v111
	v_cvt_pk_bf16_f32 v108, v108, v109
	v_cvt_pk_bf16_f32 v109, v110, v111
	ds_write_b64 v180, v[108:109] offset:112
	v_mul_f32_e32 v80, v183, v80
	v_mul_f32_e32 v81, v183, v81
	v_mul_f32_e32 v82, v183, v82
	v_mul_f32_e32 v83, v183, v83
	v_cvt_pk_bf16_f32 v80, v80, v81
	v_cvt_pk_bf16_f32 v81, v82, v83
	ds_write_b64 v180, v[80:81] offset:128
	v_mul_f32_e32 v84, v183, v84
	v_mul_f32_e32 v85, v183, v85
	v_mul_f32_e32 v86, v183, v86
	v_mul_f32_e32 v87, v183, v87
	v_cvt_pk_bf16_f32 v84, v84, v85
	v_cvt_pk_bf16_f32 v85, v86, v87
	ds_write_b64 v180, v[84:85] offset:144
	v_mul_f32_e32 v88, v183, v88
	v_mul_f32_e32 v89, v183, v89
	v_mul_f32_e32 v90, v183, v90
	v_mul_f32_e32 v91, v183, v91
	v_cvt_pk_bf16_f32 v88, v88, v89
	v_cvt_pk_bf16_f32 v89, v90, v91
	ds_write_b64 v180, v[88:89] offset:160
	v_mul_f32_e32 v92, v183, v92
	v_mul_f32_e32 v93, v183, v93
	v_mul_f32_e32 v94, v183, v94
	v_mul_f32_e32 v95, v183, v95
	v_cvt_pk_bf16_f32 v92, v92, v93
	v_cvt_pk_bf16_f32 v93, v94, v95
	ds_write_b64 v180, v[92:93] offset:176
	v_mul_f32_e32 v64, v183, v64
	v_mul_f32_e32 v65, v183, v65
	v_mul_f32_e32 v66, v183, v66
	v_mul_f32_e32 v67, v183, v67
	v_cvt_pk_bf16_f32 v64, v64, v65
	v_cvt_pk_bf16_f32 v65, v66, v67
	ds_write_b64 v180, v[64:65] offset:192
	v_mul_f32_e32 v68, v183, v68
	v_mul_f32_e32 v69, v183, v69
	v_mul_f32_e32 v70, v183, v70
	v_mul_f32_e32 v71, v183, v71
	v_cvt_pk_bf16_f32 v68, v68, v69
	v_cvt_pk_bf16_f32 v69, v70, v71
	ds_write_b64 v180, v[68:69] offset:208
	v_mul_f32_e32 v72, v183, v72
	v_mul_f32_e32 v73, v183, v73
	v_mul_f32_e32 v74, v183, v74
	v_mul_f32_e32 v75, v183, v75
	v_cvt_pk_bf16_f32 v72, v72, v73
	v_cvt_pk_bf16_f32 v73, v74, v75
	ds_write_b64 v180, v[72:73] offset:224
	v_mul_f32_e32 v76, v183, v76
	v_mul_f32_e32 v77, v183, v77
	v_mul_f32_e32 v78, v183, v78
	v_mul_f32_e32 v79, v183, v79
	v_cvt_pk_bf16_f32 v76, v76, v77
	v_cvt_pk_bf16_f32 v77, v78, v79
	ds_write_b64 v180, v[76:77] offset:240
	s_waitcnt lgkmcnt(0)
; DI bfr f2bf(float a) { return (bfr)(pack2(a, 0.f) & 0xffffu); }
; DI int crow(int reg, int h) { return (reg & 3) + 8 * (reg >> 2) + 4 * h; }
; template <int lda, class Epi>
; DI void gemm_tile(const bfr* __restrict__ A, const bfr* __restrict__ Bt, int NB, int K, int m0, int n0, char* smem, Epi epi) {
;     ...
; #pragma unroll
;   for (int i = 0; i < 2; ++i)
; #pragma unroll
;     for (int j = 0; j < 4; ++j)
; #pragma unroll
;       for (int q = 0; q < 16; ++q) {
;         int row = m0 + wr * 64 + i * 32 + crow(q, hl);
;         int col = n0 + wc * 128 + j * 32 + r;
;         epi(row, col, acc[i][j][q]);
;       }
; DI void phase_gemm_bf16out(const Params& p, const bfr* A, const bfr* Wt, bfr* C, int N, const float* ss, char* smem) {
;     ...
;   for (int t0 = blockIdx.x; t0 < 128 * ntn; t0 += gridDim.x) {
;     const int t = ((gridDim.x & 7) == 0) ? xcd_tile(t0, ntn) : t0;
;     int mt = t / ntn, nt = t % ntn;
;     gemm_tile<1024>(A, Wt, N, 1024, mt * 128, nt * 256, smem,
;               [=](int row, int col, float v) {
;                 float inv = rsqrtf(ss[row] * (1.0f / 1024.0f) + EPSF);
;                 C[(size_t)row * N + col] = f2bf(v * inv);
;               });
	ds_read_b128 v[112:115], v181
	ds_read_b128 v[116:119], v181 offset:1088
	ds_read_b128 v[120:123], v181 offset:2176
	ds_read_b128 v[124:127], v181 offset:3264
	ds_read_b128 v[96:99], v181 offset:4352
	ds_read_b128 v[100:103], v181 offset:5440
	ds_read_b128 v[104:107], v181 offset:6528
	ds_read_b128 v[108:111], v181 offset:7616
	s_add_u32 s66, s64, 0x0
	s_addc_u32 s67, s65, 0
	s_waitcnt lgkmcnt(7)
	global_store_dwordx4 v182, v[112:115], s[66:67]
	s_add_u32 s66, s64, 0x2000
	s_addc_u32 s67, s65, 0
	s_waitcnt lgkmcnt(6)
	global_store_dwordx4 v182, v[116:119], s[66:67]
	s_add_u32 s66, s64, 0x4000
	s_addc_u32 s67, s65, 0
	s_waitcnt lgkmcnt(5)
	global_store_dwordx4 v182, v[120:123], s[66:67]
	s_add_u32 s66, s64, 0x6000
	s_addc_u32 s67, s65, 0
	s_waitcnt lgkmcnt(4)
	global_store_dwordx4 v182, v[124:127], s[66:67]
	s_add_u32 s66, s64, 0x8000
	s_addc_u32 s67, s65, 0
	s_waitcnt lgkmcnt(3)
	global_store_dwordx4 v182, v[96:99], s[66:67]
	s_add_u32 s66, s64, 0xa000
	s_addc_u32 s67, s65, 0
	s_waitcnt lgkmcnt(2)
	global_store_dwordx4 v182, v[100:103], s[66:67]
	s_add_u32 s66, s64, 0xc000
	s_addc_u32 s67, s65, 0
	s_waitcnt lgkmcnt(1)
	global_store_dwordx4 v182, v[104:107], s[66:67]
	s_add_u32 s66, s64, 0xe000
	s_addc_u32 s67, s65, 0
	s_waitcnt lgkmcnt(0)
	global_store_dwordx4 v182, v[108:111], s[66:67]
	v_mul_f32_e32 v48, v184, v48
	v_mul_f32_e32 v49, v184, v49
	v_mul_f32_e32 v50, v184, v50
	v_mul_f32_e32 v51, v184, v51
	v_cvt_pk_bf16_f32 v48, v48, v49
	v_cvt_pk_bf16_f32 v49, v50, v51
	ds_write_b64 v180, v[48:49]
	v_mul_f32_e32 v52, v184, v52
	v_mul_f32_e32 v53, v184, v53
	v_mul_f32_e32 v54, v184, v54
	v_mul_f32_e32 v55, v184, v55
	v_cvt_pk_bf16_f32 v52, v52, v53
	v_cvt_pk_bf16_f32 v53, v54, v55
	ds_write_b64 v180, v[52:53] offset:16
	v_mul_f32_e32 v56, v184, v56
	v_mul_f32_e32 v57, v184, v57
	v_mul_f32_e32 v58, v184, v58
	v_mul_f32_e32 v59, v184, v59
	v_cvt_pk_bf16_f32 v56, v56, v57
	v_cvt_pk_bf16_f32 v57, v58, v59
	ds_write_b64 v180, v[56:57] offset:32
	v_mul_f32_e32 v60, v184, v60
	v_mul_f32_e32 v61, v184, v61
	v_mul_f32_e32 v62, v184, v62
	v_mul_f32_e32 v63, v184, v63
	v_cvt_pk_bf16_f32 v60, v60, v61
	v_cvt_pk_bf16_f32 v61, v62, v63
	ds_write_b64 v180, v[60:61] offset:48
	v_mul_f32_e32 v32, v184, v32
	v_mul_f32_e32 v33, v184, v33
	v_mul_f32_e32 v34, v184, v34
	v_mul_f32_e32 v35, v184, v35
	v_cvt_pk_bf16_f32 v32, v32, v33
	v_cvt_pk_bf16_f32 v33, v34, v35
	ds_write_b64 v180, v[32:33] offset:64
	v_mul_f32_e32 v36, v184, v36
	v_mul_f32_e32 v37, v184, v37
	v_mul_f32_e32 v38, v184, v38
	v_mul_f32_e32 v39, v184, v39
	v_cvt_pk_bf16_f32 v36, v36, v37
	v_cvt_pk_bf16_f32 v37, v38, v39
	ds_write_b64 v180, v[36:37] offset:80
	v_mul_f32_e32 v40, v184, v40
	v_mul_f32_e32 v41, v184, v41
	v_mul_f32_e32 v42, v184, v42
	v_mul_f32_e32 v43, v184, v43
	v_cvt_pk_bf16_f32 v40, v40, v41
	v_cvt_pk_bf16_f32 v41, v42, v43
	ds_write_b64 v180, v[40:41] offset:96
	v_mul_f32_e32 v44, v184, v44
	v_mul_f32_e32 v45, v184, v45
	v_mul_f32_e32 v46, v184, v46
	v_mul_f32_e32 v47, v184, v47
	v_cvt_pk_bf16_f32 v44, v44, v45
	v_cvt_pk_bf16_f32 v45, v46, v47
	ds_write_b64 v180, v[44:45] offset:112
	v_mul_f32_e32 v16, v184, v16
	v_mul_f32_e32 v17, v184, v17
	v_mul_f32_e32 v18, v184, v18
	v_mul_f32_e32 v19, v184, v19
	v_cvt_pk_bf16_f32 v16, v16, v17
	v_cvt_pk_bf16_f32 v17, v18, v19
	ds_write_b64 v180, v[16:17] offset:128
	v_mul_f32_e32 v20, v184, v20
	v_mul_f32_e32 v21, v184, v21
	v_mul_f32_e32 v22, v184, v22
	v_mul_f32_e32 v23, v184, v23
	v_cvt_pk_bf16_f32 v20, v20, v21
	v_cvt_pk_bf16_f32 v21, v22, v23
	ds_write_b64 v180, v[20:21] offset:144
	v_mul_f32_e32 v24, v184, v24
	v_mul_f32_e32 v25, v184, v25
	v_mul_f32_e32 v26, v184, v26
	v_mul_f32_e32 v27, v184, v27
	v_cvt_pk_bf16_f32 v24, v24, v25
	v_cvt_pk_bf16_f32 v25, v26, v27
	ds_write_b64 v180, v[24:25] offset:160
	v_mul_f32_e32 v28, v184, v28
	v_mul_f32_e32 v29, v184, v29
	v_mul_f32_e32 v30, v184, v30
	v_mul_f32_e32 v31, v184, v31
	v_cvt_pk_bf16_f32 v28, v28, v29
	v_cvt_pk_bf16_f32 v29, v30, v31
	ds_write_b64 v180, v[28:29] offset:176
	v_mul_f32_e32 v0, v184, v0
	v_mul_f32_e32 v1, v184, v1
	v_mul_f32_e32 v2, v184, v2
	v_mul_f32_e32 v3, v184, v3
	v_cvt_pk_bf16_f32 v0, v0, v1
	v_cvt_pk_bf16_f32 v1, v2, v3
	ds_write_b64 v180, v[0:1] offset:192
	v_mul_f32_e32 v4, v184, v4
	v_mul_f32_e32 v5, v184, v5
	v_mul_f32_e32 v6, v184, v6
	v_mul_f32_e32 v7, v184, v7
	v_cvt_pk_bf16_f32 v4, v4, v5
	v_cvt_pk_bf16_f32 v5, v6, v7
	ds_write_b64 v180, v[4:5] offset:208
	v_mul_f32_e32 v8, v184, v8
	v_mul_f32_e32 v9, v184, v9
	v_mul_f32_e32 v10, v184, v10
	v_mul_f32_e32 v11, v184, v11
	v_cvt_pk_bf16_f32 v8, v8, v9
	v_cvt_pk_bf16_f32 v9, v10, v11
	ds_write_b64 v180, v[8:9] offset:224
	v_mul_f32_e32 v12, v184, v12
	v_mul_f32_e32 v13, v184, v13
	v_mul_f32_e32 v14, v184, v14
	v_mul_f32_e32 v15, v184, v15
	v_cvt_pk_bf16_f32 v12, v12, v13
	v_cvt_pk_bf16_f32 v13, v14, v15
	ds_write_b64 v180, v[12:13] offset:240
	s_waitcnt lgkmcnt(0)
	ds_read_b128 v[48:51], v181
	ds_read_b128 v[52:55], v181 offset:1088
	ds_read_b128 v[56:59], v181 offset:2176
	ds_read_b128 v[60:63], v181 offset:3264
	ds_read_b128 v[32:35], v181 offset:4352
	ds_read_b128 v[36:39], v181 offset:5440
	ds_read_b128 v[40:43], v181 offset:6528
	ds_read_b128 v[44:47], v181 offset:7616
	s_add_u32 s66, s64, 0x10000
	s_addc_u32 s67, s65, 0
	s_waitcnt lgkmcnt(7)
	global_store_dwordx4 v182, v[48:51], s[66:67]
	s_add_u32 s66, s64, 0x12000
	s_addc_u32 s67, s65, 0
	s_waitcnt lgkmcnt(6)
	global_store_dwordx4 v182, v[52:55], s[66:67]
	s_add_u32 s66, s64, 0x14000
	s_addc_u32 s67, s65, 0
	s_waitcnt lgkmcnt(5)
	global_store_dwordx4 v182, v[56:59], s[66:67]
	s_add_u32 s66, s64, 0x16000
	s_addc_u32 s67, s65, 0
	s_waitcnt lgkmcnt(4)
	global_store_dwordx4 v182, v[60:63], s[66:67]
	s_add_u32 s66, s64, 0x18000
	s_addc_u32 s67, s65, 0
	s_waitcnt lgkmcnt(3)
	global_store_dwordx4 v182, v[32:35], s[66:67]
	s_add_u32 s66, s64, 0x1a000
	s_addc_u32 s67, s65, 0
	s_waitcnt lgkmcnt(2)
	global_store_dwordx4 v182, v[36:39], s[66:67]
	s_add_u32 s66, s64, 0x1c000
	s_addc_u32 s67, s65, 0
	s_waitcnt lgkmcnt(1)
	global_store_dwordx4 v182, v[40:43], s[66:67]
	s_add_u32 s66, s64, 0x1e000
	s_addc_u32 s67, s65, 0
	s_waitcnt lgkmcnt(0)
	global_store_dwordx4 v182, v[44:47], s[66:67]
	v_readlane_b32 s64, v187, 0
	v_readlane_b32 s65, v187, 1
	v_readlane_b32 s66, v187, 2
	v_readlane_b32 s67, v187, 3
	v_readlane_b32 s68, v187, 4
	v_readlane_b32 s69, v187, 5
	v_readlane_b32 s70, v187, 6
	v_readlane_b32 s71, v187, 7
	v_readlane_b32 s72, v187, 8
	v_readlane_b32 s73, v187, 9
	v_readlane_b32 s74, v187, 10
	v_readlane_b32 s75, v187, 11
	v_readlane_b32 s76, v187, 12
	v_readlane_b32 s77, v187, 13
	v_readlane_b32 s78, v187, 14
	v_readlane_b32 s79, v187, 15
	s_nop 7
	s_add_i32 s30, s30, s34
	s_cmpk_lt_i32 s30, 0x200
	s_cbranch_scc0 .LBB0_1559
	s_branch .LBB0_1546
